# nt hint on read-once f32 weight loads (weight conversion in P0/P1/P2) and on the layer-0 P4 f32 residual loads (x_prompt), on top of v43
# baseline (speedup 1.0000x reference)
; #define LAS __attribute__((address_space(3)))
; __device__ __forceinline__ void transpose_item(const float* W, int N, const float* ks, bf16_t* WT, int ldo, int orow0, int k0, int n0, LAS float* scr, int lane) {
;     f32x4 v[8];
; #pragma unroll
;     for (int i = 0; i < 8; ++i) v[i] = *(const f32x4*)(W + (size_t)(k0 + i * 4 + (lane >> 4)) * N + n0 + 4 * (lane & 15));
; #pragma unroll
;     for (int i = 0; i < 8; ++i) { const int kk = i * 4 + (lane >> 4); const float sc = ks ? ks[k0 + kk] : 1.0f; LAS float* d = scr + kk * 65 + 4 * (lane & 15);
;         d[0] = v[i][0] * sc; d[1] = v[i][1] * sc; d[2] = v[i][2] * sc; d[3] = v[i][3] * sc; }
; __device__ __forceinline__ void convert_weights(const Params& p, LAS unsigned char* lds, int first, int last, int worker, int nworkers) {
;     ...
;         if (r < WI_IN) { const int kb = r / 52, nb = r % 52; transpose_item(p.w_in + (size_t)l * DM * INW, INW, p.norm_mix + l * DM, (bf16_t*)(wb + WO_IN), DM, nb * 64, kb * 32, nb * 64, scr, lane); continue; } r -= WI_IN;
.LBB0_55:
	s_mul_hi_i32 s4, s17, 0x4ec4ec4f
	s_lshr_b32 s5, s4, 31
	s_ashr_i32 s18, s4, 11
	s_add_i32 s18, s18, s5
	s_mul_i32 s4, s18, 0xffffe600
	s_add_i32 s4, s17, s4
	s_mul_i32 s5, s4, 0x4ec5
	s_lshr_b32 s8, s5, 31
	s_ashr_i32 s5, s5, 20
	s_add_i32 s8, s5, s8
	s_mul_i32 s5, s8, 52
	v_readlane_b32 s52, v249, 4
	s_sub_i32 s4, s4, s5
	s_mul_i32 s5, s18, 0xd00000
	v_readlane_b32 s66, v249, 18
	s_sext_i32_i16 s9, s4
	s_mul_hi_i32 s4, s18, 0xd00000
	v_readlane_b32 s67, v249, 19
	s_add_u32 s19, s66, s5
	s_addc_u32 s23, s67, s4
	s_lshl_b32 s4, s18, 10
	s_ashr_i32 s5, s4, 31
	v_readlane_b32 s64, v249, 16
	s_lshl_b64 s[4:5], s[4:5], 2
	v_readlane_b32 s65, v249, 17
	s_add_u32 s10, s64, s4
	s_addc_u32 s11, s65, s5
	s_lshl_b32 s4, s9, 6
	s_ashr_i32 s5, s4, 31
	s_lshl_b32 s8, s8, 5
	s_lshl_b64 s[20:21], s[4:5], 2
	v_or_b32_e32 v40, s8, v32
	s_add_u32 s20, s19, s20
	s_addc_u32 s21, s23, s21
	v_mul_i32_i24_e32 v4, 0xd00, v40
	v_lshl_add_u64 v[0:1], s[20:21], 0, v[36:37]
	v_mul_hi_i32_i24_e32 v3, 0x3400, v40
	v_mul_i32_i24_e32 v2, 0x3400, v40
	v_ashrrev_i32_e32 v5, 31, v4
	v_lshl_add_u64 v[2:3], v[0:1], 0, v[2:3]
	v_lshl_add_u64 v[0:1], v[4:5], 2, v[0:1]
	v_add_co_u32_e32 v4, vcc, s13, v0
	v_mov_b32_e32 v38, 1.0
	s_nop 0
	v_addc_co_u32_e32 v5, vcc, 0, v1, vcc
	global_load_dwordx4 v[28:31], v[2:3], off nt
	global_load_dwordx4 v[24:27], v[4:5], off nt
	v_add_co_u32_e32 v2, vcc, s14, v0
	v_mov_b32_e32 v42, 1.0
	s_nop 0
	v_addc_co_u32_e32 v3, vcc, 0, v1, vcc
	v_add_co_u32_e32 v4, vcc, s15, v0
	v_readlane_b32 s53, v249, 5
	s_nop 0
	v_addc_co_u32_e32 v5, vcc, 0, v1, vcc
	global_load_dwordx4 v[20:23], v[2:3], off nt
	global_load_dwordx4 v[16:19], v[4:5], off nt
	v_add_co_u32_e32 v2, vcc, s16, v0
	v_readlane_b32 s54, v249, 6
	s_nop 0
	v_addc_co_u32_e32 v3, vcc, 0, v1, vcc
	v_add_co_u32_e32 v4, vcc, 0x41000, v0
	v_readlane_b32 s55, v249, 7
	s_nop 0
	v_addc_co_u32_e32 v5, vcc, 0, v1, vcc
	global_load_dwordx4 v[12:15], v[2:3], off nt
	global_load_dwordx4 v[8:11], v[4:5], off nt
	v_add_co_u32_e32 v2, vcc, 0x4e000, v0
	v_readlane_b32 s56, v249, 8
	s_nop 0
	v_addc_co_u32_e32 v3, vcc, 0, v1, vcc
	v_add_co_u32_e32 v0, vcc, 0x5b000, v0
	v_readlane_b32 s57, v249, 9
	s_nop 0
	v_addc_co_u32_e32 v1, vcc, 0, v1, vcc
	global_load_dwordx4 v[4:7], v[2:3], off nt
	s_nop 0
	global_load_dwordx4 v[0:3], v[0:1], off nt
	s_and_b64 vcc, exec, s[30:31]
	v_readlane_b32 s58, v249, 10
	v_readlane_b32 s59, v249, 11
	v_readlane_b32 s60, v249, 12
	v_readlane_b32 s61, v249, 13
	v_readlane_b32 s62, v249, 14
	v_readlane_b32 s63, v249, 15
	s_cbranch_vccnz .LBB0_57
	v_ashrrev_i32_e32 v41, 31, v40
	s_ashr_i32 s9, s8, 31
	v_lshl_add_u64 v[40:41], v[40:41], 2, s[10:11]
	v_lshl_add_u64 v[50:51], s[8:9], 0, v[32:33]
	global_load_dword v40, v[40:41], off
	v_lshl_add_u64 v[50:51], v[50:51], 2, s[10:11]
	global_load_dword v42, v[50:51], off offset:16
	s_waitcnt vmcnt(1)
	v_pk_mul_f32 v[28:29], v[28:29], v[40:41] op_sel_hi:[1,0]
	v_pk_mul_f32 v[30:31], v[30:31], v[40:41] op_sel_hi:[1,0]

; #define LAS __attribute__((address_space(3)))
; __device__ __forceinline__ unsigned cvt_pk_bf16(float lo, float hi) { unsigned r; asm volatile("v_cvt_pk_bf16_f32 %0, %1, %2" : "=v"(r) : "v"(lo), "v"(hi)); return r; }
; __device__ __forceinline__ void transpose_item(const float* W, int N, const float* ks, bf16_t* WT, int ldo, int orow0, int k0, int n0, LAS float* scr, int lane) {
;     f32x4 v[8];
; #pragma unroll
;     for (int i = 0; i < 8; ++i) v[i] = *(const f32x4*)(W + (size_t)(k0 + i * 4 + (lane >> 4)) * N + n0 + 4 * (lane & 15));
; #pragma unroll
;     for (int i = 0; i < 8; ++i) { const int kk = i * 4 + (lane >> 4); const float sc = ks ? ks[k0 + kk] : 1.0f; LAS float* d = scr + kk * 65 + 4 * (lane & 15);
;         d[0] = v[i][0] * sc; d[1] = v[i][1] * sc; d[2] = v[i][2] * sc; d[3] = v[i][3] * sc; }
;     asm volatile("s_waitcnt lgkmcnt(0)" ::: "memory");
;     const int kc = lane & 3;
; #pragma unroll
;     for (int j = 0; j < 4; ++j) { const int n = (lane >> 2) + 16 * j; const LAS float* s = scr + (8 * kc) * 65 + n;
;         u32x4 o; o.x = cvt_pk_bf16(s[0 * 65], s[1 * 65]); o.y = cvt_pk_bf16(s[2 * 65], s[3 * 65]); o.z = cvt_pk_bf16(s[4 * 65], s[5 * 65]); o.w = cvt_pk_bf16(s[6 * 65], s[7 * 65]);
;         *(u32x4*)(WT + (size_t)(orow0 + n) * ldo + k0 + 8 * kc) = o; }
;     asm volatile("s_waitcnt lgkmcnt(0)" ::: "memory");
; }
; __device__ __forceinline__ void convert_weights(const Params& p, LAS unsigned char* lds, int first, int last, int worker, int nworkers) {
;     ...
;         { const int kb = r / 16, nb = r % 16; transpose_item(p.w_down + (size_t)l * FF * DM, DM, nullptr, (bf16_t*)(wb + WO_DOWN), FF, nb * 64, kb * 32, nb * 64, scr, lane); }
.LBB0_196:
	s_mul_hi_i32 s0, s7, 0x4ec4ec4f
	s_lshr_b32 s1, s0, 31
	s_ashr_i32 s0, s0, 11
	s_add_i32 s2, s0, s1
	s_mul_i32 s0, s2, 0xffffe600
	s_add_i32 s16, s7, s0
	s_ashr_i32 s3, s2, 31
	s_mul_i32 s1, s2, 0x1b00000
	s_mul_hi_i32 s0, s2, 0x1b00000
	s_add_u32 s14, s80, s1
	s_addc_u32 s15, s82, s0
	s_cmpk_gt_i32 s16, 0x67f
	s_mov_b64 s[0:1], -1
	s_cbranch_scc0 .LBB0_218
	s_cmpk_gt_u32 s16, 0x77f
	s_cbranch_scc0 .LBB0_215
	s_cmpk_gt_u32 s16, 0x97f
	s_cbranch_scc0 .LBB0_212
	s_cmpk_gt_u32 s16, 0x147f
	s_cbranch_scc0 .LBB0_201
	v_readlane_b32 s40, v248, 54
	s_mul_i32 s1, s2, 0xb00000
	v_readlane_b32 s50, v247, 0
	s_mul_hi_i32 s0, s2, 0xb00000
	v_readlane_b32 s51, v247, 1
	s_add_u32 s1, s50, s1
	s_mul_i32 s8, s2, 0xffffcc00
	s_addc_u32 s9, s51, s0
	s_add_i32 s8, s10, s8
	s_and_b32 s0, s12, 0x3c0
	s_and_b32 s8, s8, 0x7fffffe0
	s_add_i32 s96, s8, 0xffffd700
	s_lshl_b32 s8, s0, 2
	s_add_u32 s8, s1, s8
	v_or_b32_e32 v28, s96, v32
	s_addc_u32 s9, s9, 0
	v_lshlrev_b32_e32 v96, 2, v34
	v_mov_b32_e32 v29, v97
	v_lshl_add_u64 v[30:31], s[8:9], 0, v[96:97]
	v_lshlrev_b64 v[0:1], 12, v[28:29]
	v_or_b32_e32 v96, 4, v28
	v_lshl_add_u64 v[0:1], v[30:31], 0, v[0:1]
	v_lshlrev_b64 v[4:5], 12, v[96:97]
	global_load_dwordx4 v[0:3], v[0:1], off nt
	v_lshl_add_u64 v[4:5], v[30:31], 0, v[4:5]
	v_or_b32_e32 v96, 8, v28
	global_load_dwordx4 v[4:7], v[4:5], off nt
	v_lshlrev_b64 v[8:9], 12, v[96:97]
	v_lshl_add_u64 v[8:9], v[30:31], 0, v[8:9]
	v_or_b32_e32 v96, 12, v28
	global_load_dwordx4 v[8:11], v[8:9], off nt
	v_lshlrev_b64 v[12:13], 12, v[96:97]
	v_lshl_add_u64 v[12:13], v[30:31], 0, v[12:13]
	v_or_b32_e32 v96, 16, v28
	global_load_dwordx4 v[12:15], v[12:13], off nt
	v_lshlrev_b64 v[16:17], 12, v[96:97]
	v_lshl_add_u64 v[16:17], v[30:31], 0, v[16:17]
	v_or_b32_e32 v96, 20, v28
	global_load_dwordx4 v[16:19], v[16:17], off nt
	v_lshlrev_b64 v[20:21], 12, v[96:97]
	v_lshl_add_u64 v[20:21], v[30:31], 0, v[20:21]
	v_or_b32_e32 v96, 24, v28
	global_load_dwordx4 v[20:23], v[20:21], off nt
	v_lshlrev_b64 v[24:25], 12, v[96:97]
	v_lshl_add_u64 v[24:25], v[30:31], 0, v[24:25]
	v_or_b32_e32 v96, 28, v28
	global_load_dwordx4 v[24:27], v[24:25], off nt
	v_lshlrev_b64 v[28:29], 12, v[96:97]
	v_lshl_add_u64 v[28:29], v[30:31], 0, v[28:29]
	global_load_dwordx4 v[28:31], v[28:29], off nt
	v_add_u32_e32 v38, v35, v37
	s_lshl_b64 s[8:9], s[96:97], 1
	s_add_u32 s8, s14, s8
	s_addc_u32 s9, s15, s9
	v_lshlrev_b32_e32 v96, 1, v36
	v_readlane_b32 s41, v248, 55
	v_readlane_b32 s42, v248, 56
	v_readlane_b32 s43, v248, 57
	v_readlane_b32 s44, v248, 58
	v_readlane_b32 s45, v248, 59
	v_readlane_b32 s46, v248, 60
	v_readlane_b32 s47, v248, 61
	v_readlane_b32 s48, v248, 62
	v_readlane_b32 s49, v248, 63
	v_readlane_b32 s52, v247, 2
	v_readlane_b32 s53, v247, 3
	v_readlane_b32 s54, v247, 4
	v_readlane_b32 s55, v247, 5
	s_waitcnt vmcnt(0)
	ds_write2_b32 v38, v0, v1 offset1:1
	ds_write2_b32 v38, v2, v3 offset0:2 offset1:3
	v_add_u32_e32 v0, 0x410, v38
	ds_write2_b32 v0, v4, v5 offset1:1
	v_add_u32_e32 v0, 0x418, v38
	ds_write2_b32 v0, v6, v7 offset1:1
	v_add_u32_e32 v0, 0x820, v38
	ds_write2_b32 v0, v8, v9 offset1:1
	v_add_u32_e32 v0, 0x828, v38
	ds_write2_b32 v0, v10, v11 offset1:1
	v_add_u32_e32 v0, 0xc30, v38
	ds_write2_b32 v0, v12, v13 offset1:1
	v_add_u32_e32 v0, 0xc38, v38
	ds_write2_b32 v0, v14, v15 offset1:1
	v_add_u32_e32 v0, 0x1040, v38
	ds_write2_b32 v0, v16, v17 offset1:1
	v_add_u32_e32 v0, 0x1048, v38
	ds_write2_b32 v0, v18, v19 offset1:1
	v_add_u32_e32 v0, 0x1450, v38
	ds_write2_b32 v0, v20, v21 offset1:1
	v_add_u32_e32 v0, 0x1458, v38
	ds_write2_b32 v0, v22, v23 offset1:1
	v_add_u32_e32 v0, 0x1860, v38
	ds_write2_b32 v0, v24, v25 offset1:1
	v_add_u32_e32 v0, 0x1868, v38
	ds_write2_b32 v0, v26, v27 offset1:1
	v_add_u32_e32 v0, 0x1c70, v38
	ds_write2_b32 v0, v28, v29 offset1:1
	v_add_u32_e32 v0, 0x1c78, v38
	ds_write2_b32 v0, v30, v31 offset1:1
	s_waitcnt lgkmcnt(0)
	v_lshl_add_u64 v[0:1], s[8:9], 0, v[96:97]
	s_mov_b64 s[8:9], 0x1580000
	v_lshl_add_u64 v[4:5], v[0:1], 0, s[8:9]
	ds_read2_b32 v[0:1], v43 offset1:65
	s_waitcnt lgkmcnt(0)
	v_cvt_pk_bf16_f32 v0, v0, v1
	ds_read2_b32 v[2:3], v43 offset0:130 offset1:195
	v_add_u32_e32 v8, 0x400, v43
	s_waitcnt lgkmcnt(0)
	v_cvt_pk_bf16_f32 v1, v2, v3
	ds_read2_b32 v[2:3], v8 offset0:4 offset1:69
	s_waitcnt lgkmcnt(0)
	v_cvt_pk_bf16_f32 v2, v2, v3
	ds_read2_b32 v[6:7], v8 offset0:134 offset1:199
	s_waitcnt lgkmcnt(0)
	v_cvt_pk_bf16_f32 v3, v6, v7
	v_or_b32_e32 v6, s0, v39
	v_mul_u32_u24_e32 v6, 0xb00, v6
	v_lshlrev_b32_e32 v96, 1, v6
	v_lshl_add_u64 v[6:7], v[4:5], 0, v[96:97]
	global_store_dwordx4 v[6:7], v[0:3], off
	ds_read2_b32 v[0:1], v43 offset0:16 offset1:81
	s_waitcnt lgkmcnt(0)
	v_cvt_pk_bf16_f32 v0, v0, v1
	ds_read2_b32 v[2:3], v43 offset0:146 offset1:211
	s_waitcnt lgkmcnt(0)
	v_cvt_pk_bf16_f32 v1, v2, v3
	ds_read2_b32 v[2:3], v8 offset0:20 offset1:85
	s_waitcnt lgkmcnt(0)
	v_cvt_pk_bf16_f32 v2, v2, v3
	ds_read2_b32 v[6:7], v8 offset0:150 offset1:215
	s_waitcnt lgkmcnt(0)
	v_cvt_pk_bf16_f32 v3, v6, v7
	v_or_b32_e32 v6, s0, v44
	v_mul_u32_u24_e32 v6, 0xb00, v6
	v_lshlrev_b32_e32 v96, 1, v6
	v_lshl_add_u64 v[6:7], v[4:5], 0, v[96:97]
	global_store_dwordx4 v[6:7], v[0:3], off
	ds_read2_b32 v[0:1], v43 offset0:32 offset1:97
	s_waitcnt lgkmcnt(0)
	v_cvt_pk_bf16_f32 v0, v0, v1
	ds_read2_b32 v[2:3], v43 offset0:162 offset1:227
	s_waitcnt lgkmcnt(0)
	v_cvt_pk_bf16_f32 v1, v2, v3
	ds_read2_b32 v[2:3], v8 offset0:36 offset1:101
	s_waitcnt lgkmcnt(0)
	v_cvt_pk_bf16_f32 v2, v2, v3
	ds_read2_b32 v[6:7], v8 offset0:166 offset1:231
	s_waitcnt lgkmcnt(0)
	v_cvt_pk_bf16_f32 v3, v6, v7
	v_or_b32_e32 v6, s0, v45
	v_mul_u32_u24_e32 v6, 0xb00, v6
	v_lshlrev_b32_e32 v96, 1, v6
	v_lshl_add_u64 v[6:7], v[4:5], 0, v[96:97]
	global_store_dwordx4 v[6:7], v[0:3], off
	ds_read2_b32 v[0:1], v43 offset0:48 offset1:113
	s_waitcnt lgkmcnt(0)
	v_cvt_pk_bf16_f32 v0, v0, v1
	ds_read2_b32 v[2:3], v43 offset0:178 offset1:243
	s_waitcnt lgkmcnt(0)
	v_cvt_pk_bf16_f32 v1, v2, v3
	ds_read2_b32 v[2:3], v8 offset0:52 offset1:117
	s_waitcnt lgkmcnt(0)
	v_cvt_pk_bf16_f32 v2, v2, v3
	ds_read2_b32 v[6:7], v8 offset0:182 offset1:247
	s_waitcnt lgkmcnt(0)
	v_cvt_pk_bf16_f32 v3, v6, v7
	v_or_b32_e32 v6, s0, v46
	v_mul_u32_u24_e32 v6, 0xb00, v6
	v_lshlrev_b32_e32 v96, 1, v6
	v_lshl_add_u64 v[4:5], v[4:5], 0, v[96:97]
	global_store_dwordx4 v[4:5], v[0:3], off
	s_waitcnt lgkmcnt(0)
	s_mov_b64 s[0:1], 0
; #define LAS __attribute__((address_space(3)))
; __device__ __forceinline__ void transpose_item(const float* W, int N, const float* ks, bf16_t* WT, int ldo, int orow0, int k0, int n0, LAS float* scr, int lane) {
;     f32x4 v[8];
; #pragma unroll
;     for (int i = 0; i < 8; ++i) v[i] = *(const f32x4*)(W + (size_t)(k0 + i * 4 + (lane >> 4)) * N + n0 + 4 * (lane & 15));
; #pragma unroll
;     for (int i = 0; i < 8; ++i) { const int kk = i * 4 + (lane >> 4); const float sc = ks ? ks[k0 + kk] : 1.0f; LAS float* d = scr + kk * 65 + 4 * (lane & 15);
;         d[0] = v[i][0] * sc; d[1] = v[i][1] * sc; d[2] = v[i][2] * sc; d[3] = v[i][3] * sc; }
; __device__ __forceinline__ void convert_weights(const Params& p, LAS unsigned char* lds, int first, int last, int worker, int nworkers) {
;     ...
;         if (r < WI_UP) { const int kb = r / 88, nb = r % 88; const int n0 = nb * 64; const int nn = n0 < FF ? n0 : n0 - FF; const int orow = (nn >> 7) * 256 + (n0 < FF ? 0 : 128) + (nn & 127);
;             transpose_item(p.w_up + (size_t)l * DM * FF2, FF2, p.norm_ffn + l * DM, (bf16_t*)(wb + WO_UP), DM, orow, kb * 32, n0, scr, lane); continue; } r -= WI_UP;
.LBB0_201:
	s_andn2_b64 vcc, exec, s[0:1]
	s_cbranch_vccnz .LBB0_211
	s_add_i32 s0, s16, 0xf680
	s_and_b32 s1, s0, 0xffff
	s_mul_i32 s1, s1, 0xba2f
	s_lshr_b32 s17, s1, 22
	s_mul_i32 s1, s17, 0x58
	v_readlane_b32 s40, v248, 54
	s_sub_i32 s18, s0, s1
	s_mul_i32 s1, s2, 0x1600000
	v_readlane_b32 s44, v248, 58
	s_mul_hi_i32 s0, s2, 0x1600000
	v_readlane_b32 s45, v248, 59
	s_add_u32 s19, s44, s1
	s_addc_u32 s20, s45, s0
	s_lshl_b32 s0, s2, 10
	s_ashr_i32 s1, s0, 31
	v_readlane_b32 s42, v248, 56
	s_lshl_b64 s[0:1], s[0:1], 2
	v_readlane_b32 s43, v248, 57
	s_add_u32 s8, s42, s0
	s_addc_u32 s9, s43, s1
	s_lshl_b32 s0, s18, 8
	s_lshl_b32 s17, s17, 5
	s_and_b32 s0, s0, 0x3ff00
	s_add_u32 s0, s19, s0
	v_or_b32_e32 v42, s17, v32
	s_addc_u32 s1, s20, 0
	v_lshlrev_b32_e32 v96, 2, v34
	v_lshl_add_u64 v[0:1], s[0:1], 0, v[96:97]
	s_movk_i32 s0, 0x5800
	v_mul_u32_u24_e32 v4, 0x1600, v42
	v_mad_u64_u32 v[2:3], s[0:1], v42, s0, v[0:1]
	v_lshlrev_b32_e32 v96, 2, v4
	v_lshl_add_u64 v[0:1], v[0:1], 0, v[96:97]
	s_mov_b32 s0, 0x16000
	v_add_co_u32_e32 v4, vcc, s0, v0
	s_mov_b32 s0, 0x2c000
	s_nop 0
	v_addc_co_u32_e32 v5, vcc, 0, v1, vcc
	global_load_dwordx4 v[28:31], v[2:3], off
	global_load_dwordx4 v[24:27], v[4:5], off
	v_add_co_u32_e32 v2, vcc, s0, v0
	s_mov_b32 s0, 0x42000
	s_nop 0
	v_addc_co_u32_e32 v3, vcc, 0, v1, vcc
	v_add_co_u32_e32 v4, vcc, s0, v0
	s_mov_b32 s0, 0x58000
	s_nop 0
	v_addc_co_u32_e32 v5, vcc, 0, v1, vcc
	global_load_dwordx4 v[20:23], v[2:3], off
	global_load_dwordx4 v[16:19], v[4:5], off
	v_add_co_u32_e32 v2, vcc, s0, v0
	v_readlane_b32 s20, v247, 6
	s_nop 0
	v_addc_co_u32_e32 v3, vcc, 0, v1, vcc
	v_add_co_u32_e32 v4, vcc, 0x6e000, v0
	v_readlane_b32 s21, v247, 7
	s_nop 0
	v_addc_co_u32_e32 v5, vcc, 0, v1, vcc
	global_load_dwordx4 v[12:15], v[2:3], off
	global_load_dwordx4 v[8:11], v[4:5], off
	v_add_co_u32_e32 v2, vcc, 0x84000, v0
	v_cndmask_b32_e64 v40, 0, 1, s[20:21]
	s_nop 0
	v_addc_co_u32_e32 v3, vcc, 0, v1, vcc
	v_add_co_u32_e32 v0, vcc, 0x9a000, v0
	v_mov_b32_e32 v38, 1.0
	s_nop 0
	v_addc_co_u32_e32 v1, vcc, 0, v1, vcc
	global_load_dwordx4 v[4:7], v[2:3], off
	s_nop 0
	global_load_dwordx4 v[0:3], v[0:1], off nt
	v_cmp_ne_u32_e64 s[0:1], 1, v40
	s_andn2_b64 vcc, exec, s[20:21]
	v_add_lshl_u32 v41, v32, s17, 2
	v_mov_b32_e32 v40, 1.0
	v_readlane_b32 s41, v248, 55
	v_readlane_b32 s46, v248, 60
	v_readlane_b32 s47, v248, 61
	v_readlane_b32 s48, v248, 62
	v_readlane_b32 s49, v248, 63
	v_readlane_b32 s50, v247, 0
	v_readlane_b32 s51, v247, 1
	v_readlane_b32 s52, v247, 2
	v_readlane_b32 s53, v247, 3
	v_readlane_b32 s54, v247, 4
	v_readlane_b32 s55, v247, 5
	s_cbranch_vccnz .LBB0_204
	v_lshlrev_b32_e32 v40, 2, v42
	global_load_dword v40, v40, s[8:9]
	s_waitcnt vmcnt(0)
	v_pk_mul_f32 v[28:29], v[28:29], v[40:41] op_sel_hi:[1,0]
	v_pk_mul_f32 v[30:31], v[30:31], v[40:41] op_sel_hi:[1,0]
	global_load_dword v40, v41, s[8:9] offset:16

; #define LAS __attribute__((address_space(3)))
; __device__ __forceinline__ unsigned cvt_pk_bf16(float lo, float hi) { unsigned r; asm volatile("v_cvt_pk_bf16_f32 %0, %1, %2" : "=v"(r) : "v"(lo), "v"(hi)); return r; }
; __device__ __forceinline__ void transpose_item(const float* W, int N, const float* ks, bf16_t* WT, int ldo, int orow0, int k0, int n0, LAS float* scr, int lane) {
;     f32x4 v[8];
; #pragma unroll
;     for (int i = 0; i < 8; ++i) v[i] = *(const f32x4*)(W + (size_t)(k0 + i * 4 + (lane >> 4)) * N + n0 + 4 * (lane & 15));
; #pragma unroll
;     for (int i = 0; i < 8; ++i) { const int kk = i * 4 + (lane >> 4); const float sc = ks ? ks[k0 + kk] : 1.0f; LAS float* d = scr + kk * 65 + 4 * (lane & 15);
;         d[0] = v[i][0] * sc; d[1] = v[i][1] * sc; d[2] = v[i][2] * sc; d[3] = v[i][3] * sc; }
;     asm volatile("s_waitcnt lgkmcnt(0)" ::: "memory");
;     const int kc = lane & 3;
; #pragma unroll
;     for (int j = 0; j < 4; ++j) { const int n = (lane >> 2) + 16 * j; const LAS float* s = scr + (8 * kc) * 65 + n;
;         u32x4 o; o.x = cvt_pk_bf16(s[0 * 65], s[1 * 65]); o.y = cvt_pk_bf16(s[2 * 65], s[3 * 65]); o.z = cvt_pk_bf16(s[4 * 65], s[5 * 65]); o.w = cvt_pk_bf16(s[6 * 65], s[7 * 65]);
;         *(u32x4*)(WT + (size_t)(orow0 + n) * ldo + k0 + 8 * kc) = o; }
;     asm volatile("s_waitcnt lgkmcnt(0)" ::: "memory");
; }
; __device__ __forceinline__ void convert_weights(const Params& p, LAS unsigned char* lds, int first, int last, int worker, int nworkers) {
;     ...
;         if (r < WI_OUT) { const int kb = r / 16, nb = r % 16; transpose_item(p.w_out + (size_t)l * DM * DM, DM, nullptr, (bf16_t*)(wb + WO_OUT), DM, nb * 64, kb * 32, nb * 64, scr, lane); continue; } r -= WI_OUT;
.LBB0_212:
	s_andn2_b64 vcc, exec, s[0:1]
	s_cbranch_vccnz .LBB0_214
	s_lshl_b64 s[0:1], s[2:3], 22
	v_readlane_b32 s40, v248, 54
	v_readlane_b32 s41, v248, 55
	s_add_u32 s8, s40, s0
	s_mul_i32 s9, s2, 0xffffcc00
	s_addc_u32 s1, s41, s1
	s_add_i32 s9, s10, s9
	s_and_b32 s0, s12, 0x3c0
	s_and_b32 s9, s9, 0x1fe0
	s_add_i32 s96, s9, 0xfffff100
	s_lshl_b32 s9, s0, 2
	s_add_u32 s8, s8, s9
	v_or_b32_e32 v28, s96, v32
	s_addc_u32 s9, s1, 0
	v_lshlrev_b32_e32 v96, 2, v34
	v_mov_b32_e32 v29, v97
	v_lshl_add_u64 v[30:31], s[8:9], 0, v[96:97]
	v_lshlrev_b64 v[0:1], 12, v[28:29]
	v_or_b32_e32 v96, 4, v28
	v_lshl_add_u64 v[0:1], v[30:31], 0, v[0:1]
	v_lshlrev_b64 v[4:5], 12, v[96:97]
	global_load_dwordx4 v[0:3], v[0:1], off nt
	v_lshl_add_u64 v[4:5], v[30:31], 0, v[4:5]
	v_or_b32_e32 v96, 8, v28
	global_load_dwordx4 v[4:7], v[4:5], off nt
	v_lshlrev_b64 v[8:9], 12, v[96:97]
	v_lshl_add_u64 v[8:9], v[30:31], 0, v[8:9]
	v_or_b32_e32 v96, 12, v28
	global_load_dwordx4 v[8:11], v[8:9], off nt
	v_lshlrev_b64 v[12:13], 12, v[96:97]
	v_lshl_add_u64 v[12:13], v[30:31], 0, v[12:13]
	v_or_b32_e32 v96, 16, v28
	global_load_dwordx4 v[12:15], v[12:13], off nt
	v_lshlrev_b64 v[16:17], 12, v[96:97]
	v_lshl_add_u64 v[16:17], v[30:31], 0, v[16:17]
	v_or_b32_e32 v96, 20, v28
	global_load_dwordx4 v[16:19], v[16:17], off nt
	v_lshlrev_b64 v[20:21], 12, v[96:97]
	v_lshl_add_u64 v[20:21], v[30:31], 0, v[20:21]
	v_or_b32_e32 v96, 24, v28
	global_load_dwordx4 v[20:23], v[20:21], off nt
	v_lshlrev_b64 v[24:25], 12, v[96:97]
	v_lshl_add_u64 v[24:25], v[30:31], 0, v[24:25]
	v_or_b32_e32 v96, 28, v28
	global_load_dwordx4 v[24:27], v[24:25], off nt
	v_lshlrev_b64 v[28:29], 12, v[96:97]
	v_lshl_add_u64 v[28:29], v[30:31], 0, v[28:29]
	global_load_dwordx4 v[28:31], v[28:29], off nt
	v_add_u32_e32 v38, v35, v37
	s_lshl_b64 s[8:9], s[96:97], 1
	s_add_u32 s8, s14, s8
	s_addc_u32 s9, s15, s9
	v_lshlrev_b32_e32 v96, 1, v36
	v_readlane_b32 s42, v248, 56
	v_readlane_b32 s43, v248, 57
	v_readlane_b32 s44, v248, 58
	v_readlane_b32 s45, v248, 59
	v_readlane_b32 s46, v248, 60
	v_readlane_b32 s47, v248, 61
	v_readlane_b32 s48, v248, 62
	v_readlane_b32 s49, v248, 63
	v_readlane_b32 s50, v247, 0
	v_readlane_b32 s51, v247, 1
	v_readlane_b32 s52, v247, 2
	v_readlane_b32 s53, v247, 3
	v_readlane_b32 s54, v247, 4
	v_readlane_b32 s55, v247, 5
	s_waitcnt vmcnt(0)
	ds_write2_b32 v38, v0, v1 offset1:1
	ds_write2_b32 v38, v2, v3 offset0:2 offset1:3
	v_add_u32_e32 v0, 0x410, v38
	ds_write2_b32 v0, v4, v5 offset1:1
	v_add_u32_e32 v0, 0x418, v38
	ds_write2_b32 v0, v6, v7 offset1:1
	v_add_u32_e32 v0, 0x820, v38
	ds_write2_b32 v0, v8, v9 offset1:1
	v_add_u32_e32 v0, 0x828, v38
	ds_write2_b32 v0, v10, v11 offset1:1
	v_add_u32_e32 v0, 0xc30, v38
	ds_write2_b32 v0, v12, v13 offset1:1
	v_add_u32_e32 v0, 0xc38, v38
	ds_write2_b32 v0, v14, v15 offset1:1
	v_add_u32_e32 v0, 0x1040, v38
	ds_write2_b32 v0, v16, v17 offset1:1
	v_add_u32_e32 v0, 0x1048, v38
	ds_write2_b32 v0, v18, v19 offset1:1
	v_add_u32_e32 v0, 0x1450, v38
	ds_write2_b32 v0, v20, v21 offset1:1
	v_add_u32_e32 v0, 0x1458, v38
	ds_write2_b32 v0, v22, v23 offset1:1
	v_add_u32_e32 v0, 0x1860, v38
	ds_write2_b32 v0, v24, v25 offset1:1
	v_add_u32_e32 v0, 0x1868, v38
	ds_write2_b32 v0, v26, v27 offset1:1
	v_add_u32_e32 v0, 0x1c70, v38
	ds_write2_b32 v0, v28, v29 offset1:1
	v_add_u32_e32 v0, 0x1c78, v38
	ds_write2_b32 v0, v30, v31 offset1:1
	s_waitcnt lgkmcnt(0)
	v_lshl_add_u64 v[0:1], s[8:9], 0, v[96:97]
	s_mov_b64 s[8:9], 0x880000
	v_lshl_add_u64 v[4:5], v[0:1], 0, s[8:9]
	ds_read2_b32 v[0:1], v43 offset1:65
	s_waitcnt lgkmcnt(0)
	v_cvt_pk_bf16_f32 v0, v0, v1
	ds_read2_b32 v[2:3], v43 offset0:130 offset1:195
	v_add_u32_e32 v8, 0x400, v43
	s_waitcnt lgkmcnt(0)
	v_cvt_pk_bf16_f32 v1, v2, v3
	ds_read2_b32 v[2:3], v8 offset0:4 offset1:69
	s_waitcnt lgkmcnt(0)
	v_cvt_pk_bf16_f32 v2, v2, v3
	ds_read2_b32 v[6:7], v8 offset0:134 offset1:199
	s_waitcnt lgkmcnt(0)
	v_cvt_pk_bf16_f32 v3, v6, v7
	v_or_b32_e32 v6, s0, v39
	v_lshlrev_b32_e32 v96, 11, v6
	v_lshl_add_u64 v[6:7], v[4:5], 0, v[96:97]
	global_store_dwordx4 v[6:7], v[0:3], off
	ds_read2_b32 v[0:1], v43 offset0:16 offset1:81
	s_waitcnt lgkmcnt(0)
	v_cvt_pk_bf16_f32 v0, v0, v1
	ds_read2_b32 v[2:3], v43 offset0:146 offset1:211
	s_waitcnt lgkmcnt(0)
	v_cvt_pk_bf16_f32 v1, v2, v3
	ds_read2_b32 v[2:3], v8 offset0:20 offset1:85
	s_waitcnt lgkmcnt(0)
	v_cvt_pk_bf16_f32 v2, v2, v3
	ds_read2_b32 v[6:7], v8 offset0:150 offset1:215
	s_waitcnt lgkmcnt(0)
	v_cvt_pk_bf16_f32 v3, v6, v7
	v_or_b32_e32 v6, s0, v44
	v_lshlrev_b32_e32 v96, 11, v6
	v_lshl_add_u64 v[6:7], v[4:5], 0, v[96:97]
	global_store_dwordx4 v[6:7], v[0:3], off
	ds_read2_b32 v[0:1], v43 offset0:32 offset1:97
	s_waitcnt lgkmcnt(0)
	v_cvt_pk_bf16_f32 v0, v0, v1
	ds_read2_b32 v[2:3], v43 offset0:162 offset1:227
	s_waitcnt lgkmcnt(0)
	v_cvt_pk_bf16_f32 v1, v2, v3
	ds_read2_b32 v[2:3], v8 offset0:36 offset1:101
	s_waitcnt lgkmcnt(0)
	v_cvt_pk_bf16_f32 v2, v2, v3
	ds_read2_b32 v[6:7], v8 offset0:166 offset1:231
	s_waitcnt lgkmcnt(0)
	v_cvt_pk_bf16_f32 v3, v6, v7
	v_or_b32_e32 v6, s0, v45
	v_lshlrev_b32_e32 v96, 11, v6
	v_lshl_add_u64 v[6:7], v[4:5], 0, v[96:97]
	global_store_dwordx4 v[6:7], v[0:3], off
	ds_read2_b32 v[0:1], v43 offset0:48 offset1:113
	s_waitcnt lgkmcnt(0)
	v_cvt_pk_bf16_f32 v0, v0, v1
	ds_read2_b32 v[2:3], v43 offset0:178 offset1:243
	s_waitcnt lgkmcnt(0)
	v_cvt_pk_bf16_f32 v1, v2, v3
	ds_read2_b32 v[2:3], v8 offset0:52 offset1:117
	s_waitcnt lgkmcnt(0)
	v_cvt_pk_bf16_f32 v2, v2, v3
	ds_read2_b32 v[6:7], v8 offset0:182 offset1:247
	s_waitcnt lgkmcnt(0)
	v_cvt_pk_bf16_f32 v3, v6, v7
	v_or_b32_e32 v6, s0, v46
	v_lshlrev_b32_e32 v96, 11, v6
	v_lshl_add_u64 v[4:5], v[4:5], 0, v[96:97]
	global_store_dwordx4 v[4:5], v[0:3], off
	s_waitcnt lgkmcnt(0)

; #define LAS __attribute__((address_space(3)))
; __device__ __forceinline__ unsigned cvt_pk_bf16(float lo, float hi) { unsigned r; asm volatile("v_cvt_pk_bf16_f32 %0, %1, %2" : "=v"(r) : "v"(lo), "v"(hi)); return r; }
; __device__ __forceinline__ void transpose_item(const float* W, int N, const float* ks, bf16_t* WT, int ldo, int orow0, int k0, int n0, LAS float* scr, int lane) {
;     f32x4 v[8];
; #pragma unroll
;     for (int i = 0; i < 8; ++i) v[i] = *(const f32x4*)(W + (size_t)(k0 + i * 4 + (lane >> 4)) * N + n0 + 4 * (lane & 15));
; #pragma unroll
;     for (int i = 0; i < 8; ++i) { const int kk = i * 4 + (lane >> 4); const float sc = ks ? ks[k0 + kk] : 1.0f; LAS float* d = scr + kk * 65 + 4 * (lane & 15);
;         d[0] = v[i][0] * sc; d[1] = v[i][1] * sc; d[2] = v[i][2] * sc; d[3] = v[i][3] * sc; }
;     asm volatile("s_waitcnt lgkmcnt(0)" ::: "memory");
;     const int kc = lane & 3;
; #pragma unroll
;     for (int j = 0; j < 4; ++j) { const int n = (lane >> 2) + 16 * j; const LAS float* s = scr + (8 * kc) * 65 + n;
;         u32x4 o; o.x = cvt_pk_bf16(s[0 * 65], s[1 * 65]); o.y = cvt_pk_bf16(s[2 * 65], s[3 * 65]); o.z = cvt_pk_bf16(s[4 * 65], s[5 * 65]); o.w = cvt_pk_bf16(s[6 * 65], s[7 * 65]);
;         *(u32x4*)(WT + (size_t)(orow0 + n) * ldo + k0 + 8 * kc) = o; }
;     asm volatile("s_waitcnt lgkmcnt(0)" ::: "memory");
; }
; __device__ __forceinline__ void convert_weights(const Params& p, LAS unsigned char* lds, int first, int last, int worker, int nworkers) {
;     ...
;         if (r < WI_BA) { const int kb = r / 16, nb = r % 16; transpose_item(p.w_br_attn + (size_t)l * 512 * DM, DM, nullptr, (bf16_t*)(wb + WO_MIX), 512, nb * 64, kb * 32, nb * 64, scr, lane); continue; } r -= WI_BA;
.LBB0_215:
	s_andn2_b64 vcc, exec, s[0:1]
	s_cbranch_vccnz .LBB0_217
	v_readlane_b32 s40, v249, 20
	s_lshl_b64 s[0:1], s[2:3], 21
	v_readlane_b32 s50, v249, 30
	v_readlane_b32 s51, v249, 31
	s_add_u32 s3, s50, s0
	s_addc_u32 s1, s51, s1
	s_lshl_b32 s8, s2, 10
	s_sub_i32 s8, s10, s8
	s_and_b32 s0, s12, 0x3c0
	s_and_b32 s8, s8, 0xfe0
	s_add_i32 s96, s8, 0xfffff300
	s_lshl_b32 s8, s0, 2
	s_add_u32 s8, s3, s8
	v_or_b32_e32 v28, s96, v32
	s_addc_u32 s9, s1, 0
	v_lshlrev_b32_e32 v96, 2, v34
	v_mov_b32_e32 v29, v97
	v_lshl_add_u64 v[30:31], s[8:9], 0, v[96:97]
	v_lshlrev_b64 v[0:1], 12, v[28:29]
	v_or_b32_e32 v96, 4, v28
	v_lshl_add_u64 v[0:1], v[30:31], 0, v[0:1]
	v_lshlrev_b64 v[4:5], 12, v[96:97]
	global_load_dwordx4 v[0:3], v[0:1], off nt
	v_lshl_add_u64 v[4:5], v[30:31], 0, v[4:5]
	v_or_b32_e32 v96, 8, v28
	global_load_dwordx4 v[4:7], v[4:5], off nt
	v_lshlrev_b64 v[8:9], 12, v[96:97]
	v_lshl_add_u64 v[8:9], v[30:31], 0, v[8:9]
	v_or_b32_e32 v96, 12, v28
	global_load_dwordx4 v[8:11], v[8:9], off nt
	v_lshlrev_b64 v[12:13], 12, v[96:97]
	v_lshl_add_u64 v[12:13], v[30:31], 0, v[12:13]
	v_or_b32_e32 v96, 16, v28
	global_load_dwordx4 v[12:15], v[12:13], off nt
	v_lshlrev_b64 v[16:17], 12, v[96:97]
	v_lshl_add_u64 v[16:17], v[30:31], 0, v[16:17]
	v_or_b32_e32 v96, 20, v28
	global_load_dwordx4 v[16:19], v[16:17], off nt
	v_lshlrev_b64 v[20:21], 12, v[96:97]
	v_lshl_add_u64 v[20:21], v[30:31], 0, v[20:21]
	v_or_b32_e32 v96, 24, v28
	global_load_dwordx4 v[20:23], v[20:21], off nt
	v_lshlrev_b64 v[24:25], 12, v[96:97]
	v_lshl_add_u64 v[24:25], v[30:31], 0, v[24:25]
	v_or_b32_e32 v96, 28, v28
	global_load_dwordx4 v[24:27], v[24:25], off nt
	v_lshlrev_b64 v[28:29], 12, v[96:97]
	v_lshl_add_u64 v[28:29], v[30:31], 0, v[28:29]
	global_load_dwordx4 v[28:31], v[28:29], off nt
	v_add_u32_e32 v38, v35, v37
	s_lshl_b64 s[8:9], s[96:97], 1
	s_add_u32 s8, s14, s8
	s_addc_u32 s9, s15, s9
	v_lshlrev_b32_e32 v96, 1, v36
	v_readlane_b32 s41, v249, 21
	v_readlane_b32 s42, v249, 22
	v_readlane_b32 s43, v249, 23
	v_readlane_b32 s44, v249, 24
	v_readlane_b32 s45, v249, 25
	v_readlane_b32 s46, v249, 26
	v_readlane_b32 s47, v249, 27
	v_readlane_b32 s48, v249, 28
	v_readlane_b32 s49, v249, 29
	v_readlane_b32 s52, v249, 32
	v_readlane_b32 s53, v249, 33
	v_readlane_b32 s54, v249, 34
	v_readlane_b32 s55, v249, 35
	s_waitcnt vmcnt(0)
	ds_write2_b32 v38, v0, v1 offset1:1
	ds_write2_b32 v38, v2, v3 offset0:2 offset1:3
	v_add_u32_e32 v0, 0x410, v38
	ds_write2_b32 v0, v4, v5 offset1:1
	v_add_u32_e32 v0, 0x418, v38
	ds_write2_b32 v0, v6, v7 offset1:1
	v_add_u32_e32 v0, 0x820, v38
	ds_write2_b32 v0, v8, v9 offset1:1
	v_add_u32_e32 v0, 0x828, v38
	ds_write2_b32 v0, v10, v11 offset1:1
	v_add_u32_e32 v0, 0xc30, v38
	ds_write2_b32 v0, v12, v13 offset1:1
	v_add_u32_e32 v0, 0xc38, v38
	ds_write2_b32 v0, v14, v15 offset1:1
	v_add_u32_e32 v0, 0x1040, v38
	ds_write2_b32 v0, v16, v17 offset1:1
	v_add_u32_e32 v0, 0x1048, v38
	ds_write2_b32 v0, v18, v19 offset1:1
	v_add_u32_e32 v0, 0x1450, v38
	ds_write2_b32 v0, v20, v21 offset1:1
	v_add_u32_e32 v0, 0x1458, v38
	ds_write2_b32 v0, v22, v23 offset1:1
	v_add_u32_e32 v0, 0x1860, v38
	ds_write2_b32 v0, v24, v25 offset1:1
	v_add_u32_e32 v0, 0x1868, v38
	ds_write2_b32 v0, v26, v27 offset1:1
	v_add_u32_e32 v0, 0x1c70, v38
	ds_write2_b32 v0, v28, v29 offset1:1
	v_add_u32_e32 v0, 0x1c78, v38
	ds_write2_b32 v0, v30, v31 offset1:1
	s_waitcnt lgkmcnt(0)
	v_lshl_add_u64 v[0:1], s[8:9], 0, v[96:97]
	s_mov_b64 s[8:9], 0x680000
	v_lshl_add_u64 v[4:5], v[0:1], 0, s[8:9]
	ds_read2_b32 v[0:1], v43 offset1:65
	s_waitcnt lgkmcnt(0)
	v_cvt_pk_bf16_f32 v0, v0, v1
	ds_read2_b32 v[2:3], v43 offset0:130 offset1:195
	v_add_u32_e32 v8, 0x400, v43
	s_waitcnt lgkmcnt(0)
	v_cvt_pk_bf16_f32 v1, v2, v3
	ds_read2_b32 v[2:3], v8 offset0:4 offset1:69
	s_waitcnt lgkmcnt(0)
	v_cvt_pk_bf16_f32 v2, v2, v3
	ds_read2_b32 v[6:7], v8 offset0:134 offset1:199
	s_waitcnt lgkmcnt(0)
	v_cvt_pk_bf16_f32 v3, v6, v7
	v_or_b32_e32 v6, s0, v39
	v_lshlrev_b32_e32 v96, 10, v6
	v_lshl_add_u64 v[6:7], v[4:5], 0, v[96:97]
	global_store_dwordx4 v[6:7], v[0:3], off
	ds_read2_b32 v[0:1], v43 offset0:16 offset1:81
	s_waitcnt lgkmcnt(0)
	v_cvt_pk_bf16_f32 v0, v0, v1
	ds_read2_b32 v[2:3], v43 offset0:146 offset1:211
	s_waitcnt lgkmcnt(0)
	v_cvt_pk_bf16_f32 v1, v2, v3
	ds_read2_b32 v[2:3], v8 offset0:20 offset1:85
	s_waitcnt lgkmcnt(0)
	v_cvt_pk_bf16_f32 v2, v2, v3
	ds_read2_b32 v[6:7], v8 offset0:150 offset1:215
	s_waitcnt lgkmcnt(0)
	v_cvt_pk_bf16_f32 v3, v6, v7
	v_or_b32_e32 v6, s0, v44
	v_lshlrev_b32_e32 v96, 10, v6
	v_lshl_add_u64 v[6:7], v[4:5], 0, v[96:97]
	global_store_dwordx4 v[6:7], v[0:3], off
	ds_read2_b32 v[0:1], v43 offset0:32 offset1:97
	s_waitcnt lgkmcnt(0)
	v_cvt_pk_bf16_f32 v0, v0, v1
	ds_read2_b32 v[2:3], v43 offset0:162 offset1:227
	s_waitcnt lgkmcnt(0)
	v_cvt_pk_bf16_f32 v1, v2, v3
	ds_read2_b32 v[2:3], v8 offset0:36 offset1:101
	s_waitcnt lgkmcnt(0)
	v_cvt_pk_bf16_f32 v2, v2, v3
	ds_read2_b32 v[6:7], v8 offset0:166 offset1:231
	s_waitcnt lgkmcnt(0)
	v_cvt_pk_bf16_f32 v3, v6, v7
	v_or_b32_e32 v6, s0, v45
	v_lshlrev_b32_e32 v96, 10, v6
	v_lshl_add_u64 v[6:7], v[4:5], 0, v[96:97]
	global_store_dwordx4 v[6:7], v[0:3], off
	ds_read2_b32 v[0:1], v43 offset0:48 offset1:113
	s_waitcnt lgkmcnt(0)
	v_cvt_pk_bf16_f32 v0, v0, v1
	ds_read2_b32 v[2:3], v43 offset0:178 offset1:243
	s_waitcnt lgkmcnt(0)
	v_cvt_pk_bf16_f32 v1, v2, v3
	ds_read2_b32 v[2:3], v8 offset0:52 offset1:117
	s_waitcnt lgkmcnt(0)
	v_cvt_pk_bf16_f32 v2, v2, v3
	ds_read2_b32 v[6:7], v8 offset0:182 offset1:247
	s_waitcnt lgkmcnt(0)
	v_cvt_pk_bf16_f32 v3, v6, v7
	v_or_b32_e32 v6, s0, v46
	v_lshlrev_b32_e32 v96, 10, v6
	v_lshl_add_u64 v[4:5], v[4:5], 0, v[96:97]
	global_store_dwordx4 v[4:5], v[0:3], off
	s_waitcnt lgkmcnt(0)

; #define LAS __attribute__((address_space(3)))
; __device__ __forceinline__ void transpose_item(const float* W, int N, const float* ks, bf16_t* WT, int ldo, int orow0, int k0, int n0, LAS float* scr, int lane) {
;     f32x4 v[8];
; #pragma unroll
;     for (int i = 0; i < 8; ++i) v[i] = *(const f32x4*)(W + (size_t)(k0 + i * 4 + (lane >> 4)) * N + n0 + 4 * (lane & 15));
; #pragma unroll
;     for (int i = 0; i < 8; ++i) { const int kk = i * 4 + (lane >> 4); const float sc = ks ? ks[k0 + kk] : 1.0f; LAS float* d = scr + kk * 65 + 4 * (lane & 15);
;         d[0] = v[i][0] * sc; d[1] = v[i][1] * sc; d[2] = v[i][2] * sc; d[3] = v[i][3] * sc; }
; __device__ __forceinline__ void convert_weights(const Params& p, LAS unsigned char* lds, int first, int last, int worker, int nworkers) {
;     ...
;         if (r < WI_IN) { const int kb = r / 52, nb = r % 52; transpose_item(p.w_in + (size_t)l * DM * INW, INW, p.norm_mix + l * DM, (bf16_t*)(wb + WO_IN), DM, nb * 64, kb * 32, nb * 64, scr, lane); continue; } r -= WI_IN;
.LBB0_218:
	s_andn2_b64 vcc, exec, s[0:1]
	s_cbranch_vccnz .LBB0_195
	s_mul_i32 s0, s16, 0x4ec5
	s_lshr_b32 s1, s0, 31
	s_ashr_i32 s0, s0, 20
	s_add_i32 s3, s0, s1
	s_mul_i32 s0, s3, 52
	v_readlane_b32 s40, v249, 4
	s_sub_i32 s0, s16, s0
	s_mul_i32 s1, s2, 0xd00000
	v_readlane_b32 s54, v249, 18
	s_sext_i32_i16 s16, s0
	s_mul_hi_i32 s0, s2, 0xd00000
	v_readlane_b32 s55, v249, 19
	s_add_u32 s18, s54, s1
	s_addc_u32 s19, s55, s0
	s_lshl_b32 s0, s2, 10
	s_ashr_i32 s1, s0, 31
	v_readlane_b32 s52, v249, 16
	s_lshl_b64 s[0:1], s[0:1], 2
	v_readlane_b32 s53, v249, 17
	s_add_u32 s8, s52, s0
	s_addc_u32 s9, s53, s1
	s_lshl_b32 s0, s16, 6
	s_ashr_i32 s1, s0, 31
	s_lshl_b32 s2, s3, 5
	s_lshl_b64 s[16:17], s[0:1], 2
	v_or_b32_e32 v40, s2, v32
	s_add_u32 s16, s18, s16
	s_addc_u32 s17, s19, s17
	v_lshlrev_b32_e32 v96, 2, v34
	v_mul_i32_i24_e32 v4, 0xd00, v40
	v_lshl_add_u64 v[0:1], s[16:17], 0, v[96:97]
	v_mul_hi_i32_i24_e32 v3, 0x3400, v40
	v_mul_i32_i24_e32 v2, 0x3400, v40
	v_ashrrev_i32_e32 v5, 31, v4
	v_lshl_add_u64 v[2:3], v[0:1], 0, v[2:3]
	v_lshl_add_u64 v[0:1], v[4:5], 2, v[0:1]
	s_mov_b32 s1, 0xd000
	v_add_co_u32_e32 v4, vcc, s1, v0
	s_mov_b32 s1, 0x1a000
	s_nop 0
	v_addc_co_u32_e32 v5, vcc, 0, v1, vcc
	global_load_dwordx4 v[28:31], v[2:3], off
	global_load_dwordx4 v[24:27], v[4:5], off
	v_add_co_u32_e32 v2, vcc, s1, v0
	s_mov_b32 s1, 0x27000
	s_nop 0
	v_addc_co_u32_e32 v3, vcc, 0, v1, vcc
	v_add_co_u32_e32 v4, vcc, s1, v0
	s_mov_b32 s1, 0x34000
	s_nop 0
	v_addc_co_u32_e32 v5, vcc, 0, v1, vcc
	global_load_dwordx4 v[20:23], v[2:3], off
	global_load_dwordx4 v[16:19], v[4:5], off
	v_add_co_u32_e32 v2, vcc, s1, v0
	v_readlane_b32 s16, v248, 46
	s_nop 0
	v_addc_co_u32_e32 v3, vcc, 0, v1, vcc
	v_add_co_u32_e32 v4, vcc, 0x41000, v0
	v_readlane_b32 s17, v248, 47
	s_nop 0
	v_addc_co_u32_e32 v5, vcc, 0, v1, vcc
	global_load_dwordx4 v[12:15], v[2:3], off
	global_load_dwordx4 v[8:11], v[4:5], off
	v_add_co_u32_e32 v2, vcc, 0x4e000, v0
	v_mov_b32_e32 v38, 1.0
	s_nop 0
	v_addc_co_u32_e32 v3, vcc, 0, v1, vcc
	v_add_co_u32_e32 v0, vcc, 0x5b000, v0
	v_mov_b32_e32 v42, 1.0
	s_nop 0
	v_addc_co_u32_e32 v1, vcc, 0, v1, vcc
	global_load_dwordx4 v[4:7], v[2:3], off
	s_nop 0
	global_load_dwordx4 v[0:3], v[0:1], off nt
	s_and_b64 vcc, exec, s[16:17]
	v_readlane_b32 s41, v249, 5
	v_readlane_b32 s42, v249, 6
	v_readlane_b32 s43, v249, 7
	v_readlane_b32 s44, v249, 8
	v_readlane_b32 s45, v249, 9
	v_readlane_b32 s46, v249, 10
	v_readlane_b32 s47, v249, 11
	v_readlane_b32 s48, v249, 12
	v_readlane_b32 s49, v249, 13
	v_readlane_b32 s50, v249, 14
	v_readlane_b32 s51, v249, 15
	s_cbranch_vccnz .LBB0_221
	v_ashrrev_i32_e32 v41, 31, v40
	v_lshl_add_u64 v[40:41], v[40:41], 2, s[8:9]
	global_load_dword v40, v[40:41], off
	s_ashr_i32 s3, s2, 31
	s_waitcnt vmcnt(0)
	v_pk_mul_f32 v[28:29], v[28:29], v[40:41] op_sel_hi:[1,0]
	v_pk_mul_f32 v[30:31], v[30:31], v[40:41] op_sel_hi:[1,0]
	v_lshl_add_u64 v[40:41], s[2:3], 0, v[32:33]
	v_lshl_add_u64 v[40:41], v[40:41], 2, s[8:9]
	global_load_dword v42, v[40:41], off offset:16

; #define LAS __attribute__((address_space(3)))
; __device__ __forceinline__ unsigned cvt_pk_bf16(float lo, float hi) { unsigned r; asm volatile("v_cvt_pk_bf16_f32 %0, %1, %2" : "=v"(r) : "v"(lo), "v"(hi)); return r; }
; __device__ __forceinline__ void transpose_item(const float* W, int N, const float* ks, bf16_t* WT, int ldo, int orow0, int k0, int n0, LAS float* scr, int lane) {
;     f32x4 v[8];
; #pragma unroll
;     for (int i = 0; i < 8; ++i) v[i] = *(const f32x4*)(W + (size_t)(k0 + i * 4 + (lane >> 4)) * N + n0 + 4 * (lane & 15));
; #pragma unroll
;     for (int i = 0; i < 8; ++i) { const int kk = i * 4 + (lane >> 4); const float sc = ks ? ks[k0 + kk] : 1.0f; LAS float* d = scr + kk * 65 + 4 * (lane & 15);
;         d[0] = v[i][0] * sc; d[1] = v[i][1] * sc; d[2] = v[i][2] * sc; d[3] = v[i][3] * sc; }
;     asm volatile("s_waitcnt lgkmcnt(0)" ::: "memory");
;     const int kc = lane & 3;
; #pragma unroll
;     for (int j = 0; j < 4; ++j) { const int n = (lane >> 2) + 16 * j; const LAS float* s = scr + (8 * kc) * 65 + n;
;         u32x4 o; o.x = cvt_pk_bf16(s[0 * 65], s[1 * 65]); o.y = cvt_pk_bf16(s[2 * 65], s[3 * 65]); o.z = cvt_pk_bf16(s[4 * 65], s[5 * 65]); o.w = cvt_pk_bf16(s[6 * 65], s[7 * 65]);
;         *(u32x4*)(WT + (size_t)(orow0 + n) * ldo + k0 + 8 * kc) = o; }
;     asm volatile("s_waitcnt lgkmcnt(0)" ::: "memory");
; }
; __device__ __forceinline__ void convert_weights(const Params& p, LAS unsigned char* lds, int first, int last, int worker, int nworkers) {
;     ...
;         { const int kb = r / 16, nb = r % 16; transpose_item(p.w_down + (size_t)l * FF * DM, DM, nullptr, (bf16_t*)(wb + WO_DOWN), FF, nb * 64, kb * 32, nb * 64, scr, lane); }
.LBB0_621:
	s_mul_hi_i32 s0, s7, 0x4ec4ec4f
	s_lshr_b32 s1, s0, 31
	s_ashr_i32 s0, s0, 11
	s_add_i32 s2, s0, s1
	s_mul_i32 s0, s2, 0xffffe600
	s_add_i32 s16, s7, s0
	s_ashr_i32 s3, s2, 31
	s_mul_i32 s1, s2, 0x1b00000
	s_mul_hi_i32 s0, s2, 0x1b00000
	s_add_u32 s14, s80, s1
	s_addc_u32 s15, s82, s0
	s_cmpk_gt_i32 s16, 0x67f
	s_mov_b64 s[0:1], -1
	s_cbranch_scc0 .LBB0_643
	s_cmpk_gt_u32 s16, 0x77f
	s_cbranch_scc0 .LBB0_640
	s_cmpk_gt_u32 s16, 0x97f
	s_cbranch_scc0 .LBB0_637
	s_cmpk_gt_u32 s16, 0x147f
	s_cbranch_scc0 .LBB0_626
	v_readlane_b32 s52, v248, 54
	s_mul_i32 s1, s2, 0xb00000
	v_readlane_b32 s62, v247, 0
	s_mul_hi_i32 s0, s2, 0xb00000
	v_readlane_b32 s63, v247, 1
	s_add_u32 s1, s62, s1
	s_mul_i32 s8, s2, 0xffffcc00
	s_addc_u32 s9, s63, s0
	s_add_i32 s8, s10, s8
	s_and_b32 s0, s12, 0x3c0
	s_and_b32 s8, s8, 0x7fffffe0
	s_add_i32 s96, s8, 0xffffd700
	s_lshl_b32 s8, s0, 2
	s_add_u32 s8, s1, s8
	v_or_b32_e32 v28, s96, v32
	s_addc_u32 s9, s9, 0
	v_lshlrev_b32_e32 v96, 2, v34
	v_mov_b32_e32 v29, v97
	v_lshl_add_u64 v[30:31], s[8:9], 0, v[96:97]
	v_lshlrev_b64 v[0:1], 12, v[28:29]
	v_or_b32_e32 v96, 4, v28
	v_lshl_add_u64 v[0:1], v[30:31], 0, v[0:1]
	v_lshlrev_b64 v[4:5], 12, v[96:97]
	global_load_dwordx4 v[0:3], v[0:1], off nt
	v_lshl_add_u64 v[4:5], v[30:31], 0, v[4:5]
	v_or_b32_e32 v96, 8, v28
	global_load_dwordx4 v[4:7], v[4:5], off nt
	v_lshlrev_b64 v[8:9], 12, v[96:97]
	v_lshl_add_u64 v[8:9], v[30:31], 0, v[8:9]
	v_or_b32_e32 v96, 12, v28
	global_load_dwordx4 v[8:11], v[8:9], off nt
	v_lshlrev_b64 v[12:13], 12, v[96:97]
	v_lshl_add_u64 v[12:13], v[30:31], 0, v[12:13]
	v_or_b32_e32 v96, 16, v28
	global_load_dwordx4 v[12:15], v[12:13], off nt
	v_lshlrev_b64 v[16:17], 12, v[96:97]
	v_lshl_add_u64 v[16:17], v[30:31], 0, v[16:17]
	v_or_b32_e32 v96, 20, v28
	global_load_dwordx4 v[16:19], v[16:17], off nt
	v_lshlrev_b64 v[20:21], 12, v[96:97]
	v_lshl_add_u64 v[20:21], v[30:31], 0, v[20:21]
	v_or_b32_e32 v96, 24, v28
	global_load_dwordx4 v[20:23], v[20:21], off nt
	v_lshlrev_b64 v[24:25], 12, v[96:97]
	v_lshl_add_u64 v[24:25], v[30:31], 0, v[24:25]
	v_or_b32_e32 v96, 28, v28
	global_load_dwordx4 v[24:27], v[24:25], off nt
	v_lshlrev_b64 v[28:29], 12, v[96:97]
	v_lshl_add_u64 v[28:29], v[30:31], 0, v[28:29]
	global_load_dwordx4 v[28:31], v[28:29], off nt
	v_add_u32_e32 v38, v35, v37
	s_lshl_b64 s[8:9], s[96:97], 1
	s_add_u32 s8, s14, s8
	s_addc_u32 s9, s15, s9
	v_lshlrev_b32_e32 v96, 1, v36
	v_readlane_b32 s53, v248, 55
	v_readlane_b32 s54, v248, 56
	v_readlane_b32 s55, v248, 57
	v_readlane_b32 s56, v248, 58
	v_readlane_b32 s57, v248, 59
	v_readlane_b32 s58, v248, 60
	v_readlane_b32 s59, v248, 61
	v_readlane_b32 s60, v248, 62
	v_readlane_b32 s61, v248, 63
	v_readlane_b32 s64, v247, 2
	v_readlane_b32 s65, v247, 3
	v_readlane_b32 s66, v247, 4
	v_readlane_b32 s67, v247, 5
	s_waitcnt vmcnt(0)
	ds_write2_b32 v38, v0, v1 offset1:1
	ds_write2_b32 v38, v2, v3 offset0:2 offset1:3
	v_add_u32_e32 v0, 0x410, v38
	ds_write2_b32 v0, v4, v5 offset1:1
	v_add_u32_e32 v0, 0x418, v38
	ds_write2_b32 v0, v6, v7 offset1:1
	v_add_u32_e32 v0, 0x820, v38
	ds_write2_b32 v0, v8, v9 offset1:1
	v_add_u32_e32 v0, 0x828, v38
	ds_write2_b32 v0, v10, v11 offset1:1
	v_add_u32_e32 v0, 0xc30, v38
	ds_write2_b32 v0, v12, v13 offset1:1
	v_add_u32_e32 v0, 0xc38, v38
	ds_write2_b32 v0, v14, v15 offset1:1
	v_add_u32_e32 v0, 0x1040, v38
	ds_write2_b32 v0, v16, v17 offset1:1
	v_add_u32_e32 v0, 0x1048, v38
	ds_write2_b32 v0, v18, v19 offset1:1
	v_add_u32_e32 v0, 0x1450, v38
	ds_write2_b32 v0, v20, v21 offset1:1
	v_add_u32_e32 v0, 0x1458, v38
	ds_write2_b32 v0, v22, v23 offset1:1
	v_add_u32_e32 v0, 0x1860, v38
	ds_write2_b32 v0, v24, v25 offset1:1
	v_add_u32_e32 v0, 0x1868, v38
	ds_write2_b32 v0, v26, v27 offset1:1
	v_add_u32_e32 v0, 0x1c70, v38
	ds_write2_b32 v0, v28, v29 offset1:1
	v_add_u32_e32 v0, 0x1c78, v38
	ds_write2_b32 v0, v30, v31 offset1:1
	s_waitcnt lgkmcnt(0)
	v_lshl_add_u64 v[0:1], s[8:9], 0, v[96:97]
	s_mov_b64 s[8:9], 0x1580000
	v_lshl_add_u64 v[4:5], v[0:1], 0, s[8:9]
	ds_read2_b32 v[0:1], v43 offset1:65
	s_waitcnt lgkmcnt(0)
	v_cvt_pk_bf16_f32 v0, v0, v1
	ds_read2_b32 v[2:3], v43 offset0:130 offset1:195
	v_add_u32_e32 v8, 0x400, v43
	s_waitcnt lgkmcnt(0)
	v_cvt_pk_bf16_f32 v1, v2, v3
	ds_read2_b32 v[2:3], v8 offset0:4 offset1:69
	s_waitcnt lgkmcnt(0)
	v_cvt_pk_bf16_f32 v2, v2, v3
	ds_read2_b32 v[6:7], v8 offset0:134 offset1:199
	s_waitcnt lgkmcnt(0)
	v_cvt_pk_bf16_f32 v3, v6, v7
	v_or_b32_e32 v6, s0, v39
	v_mul_u32_u24_e32 v6, 0xb00, v6
	v_lshlrev_b32_e32 v96, 1, v6
	v_lshl_add_u64 v[6:7], v[4:5], 0, v[96:97]
	global_store_dwordx4 v[6:7], v[0:3], off
	ds_read2_b32 v[0:1], v43 offset0:16 offset1:81
	s_waitcnt lgkmcnt(0)
	v_cvt_pk_bf16_f32 v0, v0, v1
	ds_read2_b32 v[2:3], v43 offset0:146 offset1:211
	s_waitcnt lgkmcnt(0)
	v_cvt_pk_bf16_f32 v1, v2, v3
	ds_read2_b32 v[2:3], v8 offset0:20 offset1:85
	s_waitcnt lgkmcnt(0)
	v_cvt_pk_bf16_f32 v2, v2, v3
	ds_read2_b32 v[6:7], v8 offset0:150 offset1:215
	s_waitcnt lgkmcnt(0)
	v_cvt_pk_bf16_f32 v3, v6, v7
	v_or_b32_e32 v6, s0, v44
	v_mul_u32_u24_e32 v6, 0xb00, v6
	v_lshlrev_b32_e32 v96, 1, v6
	v_lshl_add_u64 v[6:7], v[4:5], 0, v[96:97]
	global_store_dwordx4 v[6:7], v[0:3], off
	ds_read2_b32 v[0:1], v43 offset0:32 offset1:97
	s_waitcnt lgkmcnt(0)
	v_cvt_pk_bf16_f32 v0, v0, v1
	ds_read2_b32 v[2:3], v43 offset0:162 offset1:227
	s_waitcnt lgkmcnt(0)
	v_cvt_pk_bf16_f32 v1, v2, v3
	ds_read2_b32 v[2:3], v8 offset0:36 offset1:101
	s_waitcnt lgkmcnt(0)
	v_cvt_pk_bf16_f32 v2, v2, v3
	ds_read2_b32 v[6:7], v8 offset0:166 offset1:231
	s_waitcnt lgkmcnt(0)
	v_cvt_pk_bf16_f32 v3, v6, v7
	v_or_b32_e32 v6, s0, v45
	v_mul_u32_u24_e32 v6, 0xb00, v6
	v_lshlrev_b32_e32 v96, 1, v6
	v_lshl_add_u64 v[6:7], v[4:5], 0, v[96:97]
	global_store_dwordx4 v[6:7], v[0:3], off
	ds_read2_b32 v[0:1], v43 offset0:48 offset1:113
	s_waitcnt lgkmcnt(0)
	v_cvt_pk_bf16_f32 v0, v0, v1
	ds_read2_b32 v[2:3], v43 offset0:178 offset1:243
	s_waitcnt lgkmcnt(0)
	v_cvt_pk_bf16_f32 v1, v2, v3
	ds_read2_b32 v[2:3], v8 offset0:52 offset1:117
	s_waitcnt lgkmcnt(0)
	v_cvt_pk_bf16_f32 v2, v2, v3
	ds_read2_b32 v[6:7], v8 offset0:182 offset1:247
	s_waitcnt lgkmcnt(0)
	v_cvt_pk_bf16_f32 v3, v6, v7
	v_or_b32_e32 v6, s0, v46
	v_mul_u32_u24_e32 v6, 0xb00, v6
	v_lshlrev_b32_e32 v96, 1, v6
	v_lshl_add_u64 v[4:5], v[4:5], 0, v[96:97]
	global_store_dwordx4 v[4:5], v[0:3], off
	s_waitcnt lgkmcnt(0)
	s_mov_b64 s[0:1], 0
; #define LAS __attribute__((address_space(3)))
; __device__ __forceinline__ void transpose_item(const float* W, int N, const float* ks, bf16_t* WT, int ldo, int orow0, int k0, int n0, LAS float* scr, int lane) {
;     f32x4 v[8];
; #pragma unroll
;     for (int i = 0; i < 8; ++i) v[i] = *(const f32x4*)(W + (size_t)(k0 + i * 4 + (lane >> 4)) * N + n0 + 4 * (lane & 15));
; #pragma unroll
;     for (int i = 0; i < 8; ++i) { const int kk = i * 4 + (lane >> 4); const float sc = ks ? ks[k0 + kk] : 1.0f; LAS float* d = scr + kk * 65 + 4 * (lane & 15);
;         d[0] = v[i][0] * sc; d[1] = v[i][1] * sc; d[2] = v[i][2] * sc; d[3] = v[i][3] * sc; }
; __device__ __forceinline__ void convert_weights(const Params& p, LAS unsigned char* lds, int first, int last, int worker, int nworkers) {
;     ...
;         if (r < WI_UP) { const int kb = r / 88, nb = r % 88; const int n0 = nb * 64; const int nn = n0 < FF ? n0 : n0 - FF; const int orow = (nn >> 7) * 256 + (n0 < FF ? 0 : 128) + (nn & 127);
;             transpose_item(p.w_up + (size_t)l * DM * FF2, FF2, p.norm_ffn + l * DM, (bf16_t*)(wb + WO_UP), DM, orow, kb * 32, n0, scr, lane); continue; } r -= WI_UP;
.LBB0_626:
	s_andn2_b64 vcc, exec, s[0:1]
	s_cbranch_vccnz .LBB0_636
	s_add_i32 s0, s16, 0xf680
	s_and_b32 s1, s0, 0xffff
	s_mul_i32 s1, s1, 0xba2f
	s_lshr_b32 s17, s1, 22
	s_mul_i32 s1, s17, 0x58
	v_readlane_b32 s52, v248, 54
	s_sub_i32 s18, s0, s1
	s_mul_i32 s1, s2, 0x1600000
	v_readlane_b32 s56, v248, 58
	s_mul_hi_i32 s0, s2, 0x1600000
	v_readlane_b32 s57, v248, 59
	s_add_u32 s19, s56, s1
	s_addc_u32 s20, s57, s0
	s_lshl_b32 s0, s2, 10
	s_ashr_i32 s1, s0, 31
	v_readlane_b32 s54, v248, 56
	s_lshl_b64 s[0:1], s[0:1], 2
	v_readlane_b32 s55, v248, 57
	s_add_u32 s8, s54, s0
	s_addc_u32 s9, s55, s1
	s_lshl_b32 s0, s18, 8
	s_lshl_b32 s17, s17, 5
	s_and_b32 s0, s0, 0x3ff00
	s_add_u32 s0, s19, s0
	v_or_b32_e32 v42, s17, v32
	s_addc_u32 s1, s20, 0
	v_lshlrev_b32_e32 v96, 2, v34
	v_lshl_add_u64 v[0:1], s[0:1], 0, v[96:97]
	s_movk_i32 s0, 0x5800
	v_mul_u32_u24_e32 v4, 0x1600, v42
	v_mad_u64_u32 v[2:3], s[0:1], v42, s0, v[0:1]
	v_lshlrev_b32_e32 v96, 2, v4
	v_lshl_add_u64 v[0:1], v[0:1], 0, v[96:97]
	s_mov_b32 s0, 0x16000
	v_add_co_u32_e32 v4, vcc, s0, v0
	s_mov_b32 s0, 0x2c000
	s_nop 0
	v_addc_co_u32_e32 v5, vcc, 0, v1, vcc
	global_load_dwordx4 v[28:31], v[2:3], off
	global_load_dwordx4 v[24:27], v[4:5], off
	v_add_co_u32_e32 v2, vcc, s0, v0
	s_mov_b32 s0, 0x42000
	s_nop 0
	v_addc_co_u32_e32 v3, vcc, 0, v1, vcc
	v_add_co_u32_e32 v4, vcc, s0, v0
	s_mov_b32 s0, 0x58000
	s_nop 0
	v_addc_co_u32_e32 v5, vcc, 0, v1, vcc
	global_load_dwordx4 v[20:23], v[2:3], off
	global_load_dwordx4 v[16:19], v[4:5], off
	v_add_co_u32_e32 v2, vcc, s0, v0
	v_readlane_b32 s20, v247, 6
	s_nop 0
	v_addc_co_u32_e32 v3, vcc, 0, v1, vcc
	v_add_co_u32_e32 v4, vcc, 0x6e000, v0
	v_readlane_b32 s21, v247, 7
	s_nop 0
	v_addc_co_u32_e32 v5, vcc, 0, v1, vcc
	global_load_dwordx4 v[12:15], v[2:3], off
	global_load_dwordx4 v[8:11], v[4:5], off
	v_add_co_u32_e32 v2, vcc, 0x84000, v0
	v_cndmask_b32_e64 v40, 0, 1, s[20:21]
	s_nop 0
	v_addc_co_u32_e32 v3, vcc, 0, v1, vcc
	v_add_co_u32_e32 v0, vcc, 0x9a000, v0
	v_mov_b32_e32 v38, 1.0
	s_nop 0
	v_addc_co_u32_e32 v1, vcc, 0, v1, vcc
	global_load_dwordx4 v[4:7], v[2:3], off
	s_nop 0
	global_load_dwordx4 v[0:3], v[0:1], off nt
	v_cmp_ne_u32_e64 s[0:1], 1, v40
	s_andn2_b64 vcc, exec, s[20:21]
	v_add_lshl_u32 v41, v32, s17, 2
	v_mov_b32_e32 v40, 1.0
	v_readlane_b32 s53, v248, 55
	v_readlane_b32 s58, v248, 60
	v_readlane_b32 s59, v248, 61
	v_readlane_b32 s60, v248, 62
	v_readlane_b32 s61, v248, 63
	v_readlane_b32 s62, v247, 0
	v_readlane_b32 s63, v247, 1
	v_readlane_b32 s64, v247, 2
	v_readlane_b32 s65, v247, 3
	v_readlane_b32 s66, v247, 4
	v_readlane_b32 s67, v247, 5
	s_cbranch_vccnz .LBB0_629
	v_lshlrev_b32_e32 v40, 2, v42
	global_load_dword v40, v40, s[8:9]
	s_waitcnt vmcnt(0)
	v_pk_mul_f32 v[28:29], v[28:29], v[40:41] op_sel_hi:[1,0]
	v_pk_mul_f32 v[30:31], v[30:31], v[40:41] op_sel_hi:[1,0]
	global_load_dword v40, v41, s[8:9] offset:16

; #define LAS __attribute__((address_space(3)))
; __device__ __forceinline__ unsigned cvt_pk_bf16(float lo, float hi) { unsigned r; asm volatile("v_cvt_pk_bf16_f32 %0, %1, %2" : "=v"(r) : "v"(lo), "v"(hi)); return r; }
; __device__ __forceinline__ void transpose_item(const float* W, int N, const float* ks, bf16_t* WT, int ldo, int orow0, int k0, int n0, LAS float* scr, int lane) {
;     f32x4 v[8];
; #pragma unroll
;     for (int i = 0; i < 8; ++i) v[i] = *(const f32x4*)(W + (size_t)(k0 + i * 4 + (lane >> 4)) * N + n0 + 4 * (lane & 15));
; #pragma unroll
;     for (int i = 0; i < 8; ++i) { const int kk = i * 4 + (lane >> 4); const float sc = ks ? ks[k0 + kk] : 1.0f; LAS float* d = scr + kk * 65 + 4 * (lane & 15);
;         d[0] = v[i][0] * sc; d[1] = v[i][1] * sc; d[2] = v[i][2] * sc; d[3] = v[i][3] * sc; }
;     asm volatile("s_waitcnt lgkmcnt(0)" ::: "memory");
;     const int kc = lane & 3;
; #pragma unroll
;     for (int j = 0; j < 4; ++j) { const int n = (lane >> 2) + 16 * j; const LAS float* s = scr + (8 * kc) * 65 + n;
;         u32x4 o; o.x = cvt_pk_bf16(s[0 * 65], s[1 * 65]); o.y = cvt_pk_bf16(s[2 * 65], s[3 * 65]); o.z = cvt_pk_bf16(s[4 * 65], s[5 * 65]); o.w = cvt_pk_bf16(s[6 * 65], s[7 * 65]);
;         *(u32x4*)(WT + (size_t)(orow0 + n) * ldo + k0 + 8 * kc) = o; }
;     asm volatile("s_waitcnt lgkmcnt(0)" ::: "memory");
; }
; __device__ __forceinline__ void convert_weights(const Params& p, LAS unsigned char* lds, int first, int last, int worker, int nworkers) {
;     ...
;         if (r < WI_OUT) { const int kb = r / 16, nb = r % 16; transpose_item(p.w_out + (size_t)l * DM * DM, DM, nullptr, (bf16_t*)(wb + WO_OUT), DM, nb * 64, kb * 32, nb * 64, scr, lane); continue; } r -= WI_OUT;
.LBB0_637:
	s_andn2_b64 vcc, exec, s[0:1]
	s_cbranch_vccnz .LBB0_639
	s_lshl_b64 s[0:1], s[2:3], 22
	v_readlane_b32 s52, v248, 54
	v_readlane_b32 s53, v248, 55
	s_add_u32 s8, s52, s0
	s_mul_i32 s9, s2, 0xffffcc00
	s_addc_u32 s1, s53, s1
	s_add_i32 s9, s10, s9
	s_and_b32 s0, s12, 0x3c0
	s_and_b32 s9, s9, 0x1fe0
	s_add_i32 s96, s9, 0xfffff100
	s_lshl_b32 s9, s0, 2
	s_add_u32 s8, s8, s9
	v_or_b32_e32 v28, s96, v32
	s_addc_u32 s9, s1, 0
	v_lshlrev_b32_e32 v96, 2, v34
	v_mov_b32_e32 v29, v97
	v_lshl_add_u64 v[30:31], s[8:9], 0, v[96:97]
	v_lshlrev_b64 v[0:1], 12, v[28:29]
	v_or_b32_e32 v96, 4, v28
	v_lshl_add_u64 v[0:1], v[30:31], 0, v[0:1]
	v_lshlrev_b64 v[4:5], 12, v[96:97]
	global_load_dwordx4 v[0:3], v[0:1], off nt
	v_lshl_add_u64 v[4:5], v[30:31], 0, v[4:5]
	v_or_b32_e32 v96, 8, v28
	global_load_dwordx4 v[4:7], v[4:5], off nt
	v_lshlrev_b64 v[8:9], 12, v[96:97]
	v_lshl_add_u64 v[8:9], v[30:31], 0, v[8:9]
	v_or_b32_e32 v96, 12, v28
	global_load_dwordx4 v[8:11], v[8:9], off nt
	v_lshlrev_b64 v[12:13], 12, v[96:97]
	v_lshl_add_u64 v[12:13], v[30:31], 0, v[12:13]
	v_or_b32_e32 v96, 16, v28
	global_load_dwordx4 v[12:15], v[12:13], off nt
	v_lshlrev_b64 v[16:17], 12, v[96:97]
	v_lshl_add_u64 v[16:17], v[30:31], 0, v[16:17]
	v_or_b32_e32 v96, 20, v28
	global_load_dwordx4 v[16:19], v[16:17], off nt
	v_lshlrev_b64 v[20:21], 12, v[96:97]
	v_lshl_add_u64 v[20:21], v[30:31], 0, v[20:21]
	v_or_b32_e32 v96, 24, v28
	global_load_dwordx4 v[20:23], v[20:21], off nt
	v_lshlrev_b64 v[24:25], 12, v[96:97]
	v_lshl_add_u64 v[24:25], v[30:31], 0, v[24:25]
	v_or_b32_e32 v96, 28, v28
	global_load_dwordx4 v[24:27], v[24:25], off nt
	v_lshlrev_b64 v[28:29], 12, v[96:97]
	v_lshl_add_u64 v[28:29], v[30:31], 0, v[28:29]
	global_load_dwordx4 v[28:31], v[28:29], off nt
	v_add_u32_e32 v38, v35, v37
	s_lshl_b64 s[8:9], s[96:97], 1
	s_add_u32 s8, s14, s8
	s_addc_u32 s9, s15, s9
	v_lshlrev_b32_e32 v96, 1, v36
	v_readlane_b32 s54, v248, 56
	v_readlane_b32 s55, v248, 57
	v_readlane_b32 s56, v248, 58
	v_readlane_b32 s57, v248, 59
	v_readlane_b32 s58, v248, 60
	v_readlane_b32 s59, v248, 61
	v_readlane_b32 s60, v248, 62
	v_readlane_b32 s61, v248, 63
	v_readlane_b32 s62, v247, 0
	v_readlane_b32 s63, v247, 1
	v_readlane_b32 s64, v247, 2
	v_readlane_b32 s65, v247, 3
	v_readlane_b32 s66, v247, 4
	v_readlane_b32 s67, v247, 5
	s_waitcnt vmcnt(0)
	ds_write2_b32 v38, v0, v1 offset1:1
	ds_write2_b32 v38, v2, v3 offset0:2 offset1:3
	v_add_u32_e32 v0, 0x410, v38
	ds_write2_b32 v0, v4, v5 offset1:1
	v_add_u32_e32 v0, 0x418, v38
	ds_write2_b32 v0, v6, v7 offset1:1
	v_add_u32_e32 v0, 0x820, v38
	ds_write2_b32 v0, v8, v9 offset1:1
	v_add_u32_e32 v0, 0x828, v38
	ds_write2_b32 v0, v10, v11 offset1:1
	v_add_u32_e32 v0, 0xc30, v38
	ds_write2_b32 v0, v12, v13 offset1:1
	v_add_u32_e32 v0, 0xc38, v38
	ds_write2_b32 v0, v14, v15 offset1:1
	v_add_u32_e32 v0, 0x1040, v38
	ds_write2_b32 v0, v16, v17 offset1:1
	v_add_u32_e32 v0, 0x1048, v38
	ds_write2_b32 v0, v18, v19 offset1:1
	v_add_u32_e32 v0, 0x1450, v38
	ds_write2_b32 v0, v20, v21 offset1:1
	v_add_u32_e32 v0, 0x1458, v38
	ds_write2_b32 v0, v22, v23 offset1:1
	v_add_u32_e32 v0, 0x1860, v38
	ds_write2_b32 v0, v24, v25 offset1:1
	v_add_u32_e32 v0, 0x1868, v38
	ds_write2_b32 v0, v26, v27 offset1:1
	v_add_u32_e32 v0, 0x1c70, v38
	ds_write2_b32 v0, v28, v29 offset1:1
	v_add_u32_e32 v0, 0x1c78, v38
	ds_write2_b32 v0, v30, v31 offset1:1
	s_waitcnt lgkmcnt(0)
	v_lshl_add_u64 v[0:1], s[8:9], 0, v[96:97]
	s_mov_b64 s[8:9], 0x880000
	v_lshl_add_u64 v[4:5], v[0:1], 0, s[8:9]
	ds_read2_b32 v[0:1], v43 offset1:65
	s_waitcnt lgkmcnt(0)
	v_cvt_pk_bf16_f32 v0, v0, v1
	ds_read2_b32 v[2:3], v43 offset0:130 offset1:195
	v_add_u32_e32 v8, 0x400, v43
	s_waitcnt lgkmcnt(0)
	v_cvt_pk_bf16_f32 v1, v2, v3
	ds_read2_b32 v[2:3], v8 offset0:4 offset1:69
	s_waitcnt lgkmcnt(0)
	v_cvt_pk_bf16_f32 v2, v2, v3
	ds_read2_b32 v[6:7], v8 offset0:134 offset1:199
	s_waitcnt lgkmcnt(0)
	v_cvt_pk_bf16_f32 v3, v6, v7
	v_or_b32_e32 v6, s0, v39
	v_lshlrev_b32_e32 v96, 11, v6
	v_lshl_add_u64 v[6:7], v[4:5], 0, v[96:97]
	global_store_dwordx4 v[6:7], v[0:3], off
	ds_read2_b32 v[0:1], v43 offset0:16 offset1:81
	s_waitcnt lgkmcnt(0)
	v_cvt_pk_bf16_f32 v0, v0, v1
	ds_read2_b32 v[2:3], v43 offset0:146 offset1:211
	s_waitcnt lgkmcnt(0)
	v_cvt_pk_bf16_f32 v1, v2, v3
	ds_read2_b32 v[2:3], v8 offset0:20 offset1:85
	s_waitcnt lgkmcnt(0)
	v_cvt_pk_bf16_f32 v2, v2, v3
	ds_read2_b32 v[6:7], v8 offset0:150 offset1:215
	s_waitcnt lgkmcnt(0)
	v_cvt_pk_bf16_f32 v3, v6, v7
	v_or_b32_e32 v6, s0, v44
	v_lshlrev_b32_e32 v96, 11, v6
	v_lshl_add_u64 v[6:7], v[4:5], 0, v[96:97]
	global_store_dwordx4 v[6:7], v[0:3], off
	ds_read2_b32 v[0:1], v43 offset0:32 offset1:97
	s_waitcnt lgkmcnt(0)
	v_cvt_pk_bf16_f32 v0, v0, v1
	ds_read2_b32 v[2:3], v43 offset0:162 offset1:227
	s_waitcnt lgkmcnt(0)
	v_cvt_pk_bf16_f32 v1, v2, v3
	ds_read2_b32 v[2:3], v8 offset0:36 offset1:101
	s_waitcnt lgkmcnt(0)
	v_cvt_pk_bf16_f32 v2, v2, v3
	ds_read2_b32 v[6:7], v8 offset0:166 offset1:231
	s_waitcnt lgkmcnt(0)
	v_cvt_pk_bf16_f32 v3, v6, v7
	v_or_b32_e32 v6, s0, v45
	v_lshlrev_b32_e32 v96, 11, v6
	v_lshl_add_u64 v[6:7], v[4:5], 0, v[96:97]
	global_store_dwordx4 v[6:7], v[0:3], off
	ds_read2_b32 v[0:1], v43 offset0:48 offset1:113
	s_waitcnt lgkmcnt(0)
	v_cvt_pk_bf16_f32 v0, v0, v1
	ds_read2_b32 v[2:3], v43 offset0:178 offset1:243
	s_waitcnt lgkmcnt(0)
	v_cvt_pk_bf16_f32 v1, v2, v3
	ds_read2_b32 v[2:3], v8 offset0:52 offset1:117
	s_waitcnt lgkmcnt(0)
	v_cvt_pk_bf16_f32 v2, v2, v3
	ds_read2_b32 v[6:7], v8 offset0:182 offset1:247
	s_waitcnt lgkmcnt(0)
	v_cvt_pk_bf16_f32 v3, v6, v7
	v_or_b32_e32 v6, s0, v46
	v_lshlrev_b32_e32 v96, 11, v6
	v_lshl_add_u64 v[4:5], v[4:5], 0, v[96:97]
	global_store_dwordx4 v[4:5], v[0:3], off
	s_waitcnt lgkmcnt(0)

; #define LAS __attribute__((address_space(3)))
; __device__ __forceinline__ unsigned cvt_pk_bf16(float lo, float hi) { unsigned r; asm volatile("v_cvt_pk_bf16_f32 %0, %1, %2" : "=v"(r) : "v"(lo), "v"(hi)); return r; }
; __device__ __forceinline__ void transpose_item(const float* W, int N, const float* ks, bf16_t* WT, int ldo, int orow0, int k0, int n0, LAS float* scr, int lane) {
;     f32x4 v[8];
; #pragma unroll
;     for (int i = 0; i < 8; ++i) v[i] = *(const f32x4*)(W + (size_t)(k0 + i * 4 + (lane >> 4)) * N + n0 + 4 * (lane & 15));
; #pragma unroll
;     for (int i = 0; i < 8; ++i) { const int kk = i * 4 + (lane >> 4); const float sc = ks ? ks[k0 + kk] : 1.0f; LAS float* d = scr + kk * 65 + 4 * (lane & 15);
;         d[0] = v[i][0] * sc; d[1] = v[i][1] * sc; d[2] = v[i][2] * sc; d[3] = v[i][3] * sc; }
;     asm volatile("s_waitcnt lgkmcnt(0)" ::: "memory");
;     const int kc = lane & 3;
; #pragma unroll
;     for (int j = 0; j < 4; ++j) { const int n = (lane >> 2) + 16 * j; const LAS float* s = scr + (8 * kc) * 65 + n;
;         u32x4 o; o.x = cvt_pk_bf16(s[0 * 65], s[1 * 65]); o.y = cvt_pk_bf16(s[2 * 65], s[3 * 65]); o.z = cvt_pk_bf16(s[4 * 65], s[5 * 65]); o.w = cvt_pk_bf16(s[6 * 65], s[7 * 65]);
;         *(u32x4*)(WT + (size_t)(orow0 + n) * ldo + k0 + 8 * kc) = o; }
;     asm volatile("s_waitcnt lgkmcnt(0)" ::: "memory");
; }
; __device__ __forceinline__ void convert_weights(const Params& p, LAS unsigned char* lds, int first, int last, int worker, int nworkers) {
;     ...
;         if (r < WI_BA) { const int kb = r / 16, nb = r % 16; transpose_item(p.w_br_attn + (size_t)l * 512 * DM, DM, nullptr, (bf16_t*)(wb + WO_MIX), 512, nb * 64, kb * 32, nb * 64, scr, lane); continue; } r -= WI_BA;
.LBB0_640:
	s_andn2_b64 vcc, exec, s[0:1]
	s_cbranch_vccnz .LBB0_642
	v_readlane_b32 s52, v249, 20
	v_readlane_b32 s62, v249, 30
	v_readlane_b32 s63, v249, 31
	s_lshl_b64 s[0:1], s[2:3], 21
	s_mov_b64 s[50:51], s[62:63]
	s_add_u32 s3, s50, s0
	s_addc_u32 s1, s51, s1
	s_lshl_b32 s8, s2, 10
	s_sub_i32 s8, s10, s8
	s_and_b32 s0, s12, 0x3c0
	s_and_b32 s8, s8, 0xfe0
	s_add_i32 s96, s8, 0xfffff300
	s_lshl_b32 s8, s0, 2
	s_add_u32 s8, s3, s8
	v_or_b32_e32 v28, s96, v32
	s_addc_u32 s9, s1, 0
	v_lshlrev_b32_e32 v96, 2, v34
	v_mov_b32_e32 v29, v97
	v_lshl_add_u64 v[30:31], s[8:9], 0, v[96:97]
	v_lshlrev_b64 v[0:1], 12, v[28:29]
	v_or_b32_e32 v96, 4, v28
	v_lshl_add_u64 v[0:1], v[30:31], 0, v[0:1]
	v_lshlrev_b64 v[4:5], 12, v[96:97]
	global_load_dwordx4 v[0:3], v[0:1], off nt
	v_lshl_add_u64 v[4:5], v[30:31], 0, v[4:5]
	v_or_b32_e32 v96, 8, v28
	global_load_dwordx4 v[4:7], v[4:5], off nt
	v_lshlrev_b64 v[8:9], 12, v[96:97]
	v_lshl_add_u64 v[8:9], v[30:31], 0, v[8:9]
	v_or_b32_e32 v96, 12, v28
	global_load_dwordx4 v[8:11], v[8:9], off nt
	v_lshlrev_b64 v[12:13], 12, v[96:97]
	v_lshl_add_u64 v[12:13], v[30:31], 0, v[12:13]
	v_or_b32_e32 v96, 16, v28
	global_load_dwordx4 v[12:15], v[12:13], off nt
	v_lshlrev_b64 v[16:17], 12, v[96:97]
	v_lshl_add_u64 v[16:17], v[30:31], 0, v[16:17]
	v_or_b32_e32 v96, 20, v28
	global_load_dwordx4 v[16:19], v[16:17], off nt
	v_lshlrev_b64 v[20:21], 12, v[96:97]
	v_lshl_add_u64 v[20:21], v[30:31], 0, v[20:21]
	v_or_b32_e32 v96, 24, v28
	global_load_dwordx4 v[20:23], v[20:21], off nt
	v_lshlrev_b64 v[24:25], 12, v[96:97]
	v_lshl_add_u64 v[24:25], v[30:31], 0, v[24:25]
	v_or_b32_e32 v96, 28, v28
	global_load_dwordx4 v[24:27], v[24:25], off nt
	v_lshlrev_b64 v[28:29], 12, v[96:97]
	v_lshl_add_u64 v[28:29], v[30:31], 0, v[28:29]
	global_load_dwordx4 v[28:31], v[28:29], off nt
	v_add_u32_e32 v38, v35, v37
	s_lshl_b64 s[8:9], s[96:97], 1
	s_add_u32 s8, s14, s8
	s_addc_u32 s9, s15, s9
	v_lshlrev_b32_e32 v96, 1, v36
	v_readlane_b32 s53, v249, 21
	v_readlane_b32 s54, v249, 22
	v_readlane_b32 s55, v249, 23
	v_readlane_b32 s56, v249, 24
	v_readlane_b32 s57, v249, 25
	v_readlane_b32 s58, v249, 26
	v_readlane_b32 s59, v249, 27
	v_readlane_b32 s60, v249, 28
	v_readlane_b32 s61, v249, 29
	v_readlane_b32 s64, v249, 32
	v_readlane_b32 s65, v249, 33
	v_readlane_b32 s66, v249, 34
	v_readlane_b32 s67, v249, 35
	s_waitcnt vmcnt(0)
	ds_write2_b32 v38, v0, v1 offset1:1
	ds_write2_b32 v38, v2, v3 offset0:2 offset1:3
	v_add_u32_e32 v0, 0x410, v38
	ds_write2_b32 v0, v4, v5 offset1:1
	v_add_u32_e32 v0, 0x418, v38
	ds_write2_b32 v0, v6, v7 offset1:1
	v_add_u32_e32 v0, 0x820, v38
	ds_write2_b32 v0, v8, v9 offset1:1
	v_add_u32_e32 v0, 0x828, v38
	ds_write2_b32 v0, v10, v11 offset1:1
	v_add_u32_e32 v0, 0xc30, v38
	ds_write2_b32 v0, v12, v13 offset1:1
	v_add_u32_e32 v0, 0xc38, v38
	ds_write2_b32 v0, v14, v15 offset1:1
	v_add_u32_e32 v0, 0x1040, v38
	ds_write2_b32 v0, v16, v17 offset1:1
	v_add_u32_e32 v0, 0x1048, v38
	ds_write2_b32 v0, v18, v19 offset1:1
	v_add_u32_e32 v0, 0x1450, v38
	ds_write2_b32 v0, v20, v21 offset1:1
	v_add_u32_e32 v0, 0x1458, v38
	ds_write2_b32 v0, v22, v23 offset1:1
	v_add_u32_e32 v0, 0x1860, v38
	ds_write2_b32 v0, v24, v25 offset1:1
	v_add_u32_e32 v0, 0x1868, v38
	ds_write2_b32 v0, v26, v27 offset1:1
	v_add_u32_e32 v0, 0x1c70, v38
	ds_write2_b32 v0, v28, v29 offset1:1
	v_add_u32_e32 v0, 0x1c78, v38
	ds_write2_b32 v0, v30, v31 offset1:1
	s_waitcnt lgkmcnt(0)
	v_lshl_add_u64 v[0:1], s[8:9], 0, v[96:97]
	s_mov_b64 s[8:9], 0x680000
	v_lshl_add_u64 v[4:5], v[0:1], 0, s[8:9]
	ds_read2_b32 v[0:1], v43 offset1:65
	s_waitcnt lgkmcnt(0)
	v_cvt_pk_bf16_f32 v0, v0, v1
	ds_read2_b32 v[2:3], v43 offset0:130 offset1:195
	v_add_u32_e32 v8, 0x400, v43
	s_waitcnt lgkmcnt(0)
	v_cvt_pk_bf16_f32 v1, v2, v3
	ds_read2_b32 v[2:3], v8 offset0:4 offset1:69
	s_waitcnt lgkmcnt(0)
	v_cvt_pk_bf16_f32 v2, v2, v3
	ds_read2_b32 v[6:7], v8 offset0:134 offset1:199
	s_waitcnt lgkmcnt(0)
	v_cvt_pk_bf16_f32 v3, v6, v7
	v_or_b32_e32 v6, s0, v39
	v_lshlrev_b32_e32 v96, 10, v6
	v_lshl_add_u64 v[6:7], v[4:5], 0, v[96:97]
	global_store_dwordx4 v[6:7], v[0:3], off
	ds_read2_b32 v[0:1], v43 offset0:16 offset1:81
	s_waitcnt lgkmcnt(0)
	v_cvt_pk_bf16_f32 v0, v0, v1
	ds_read2_b32 v[2:3], v43 offset0:146 offset1:211
	s_waitcnt lgkmcnt(0)
	v_cvt_pk_bf16_f32 v1, v2, v3
	ds_read2_b32 v[2:3], v8 offset0:20 offset1:85
	s_waitcnt lgkmcnt(0)
	v_cvt_pk_bf16_f32 v2, v2, v3
	ds_read2_b32 v[6:7], v8 offset0:150 offset1:215
	s_waitcnt lgkmcnt(0)
	v_cvt_pk_bf16_f32 v3, v6, v7
	v_or_b32_e32 v6, s0, v44
	v_lshlrev_b32_e32 v96, 10, v6
	v_lshl_add_u64 v[6:7], v[4:5], 0, v[96:97]
	global_store_dwordx4 v[6:7], v[0:3], off
	ds_read2_b32 v[0:1], v43 offset0:32 offset1:97
	s_waitcnt lgkmcnt(0)
	v_cvt_pk_bf16_f32 v0, v0, v1
	ds_read2_b32 v[2:3], v43 offset0:162 offset1:227
	s_waitcnt lgkmcnt(0)
	v_cvt_pk_bf16_f32 v1, v2, v3
	ds_read2_b32 v[2:3], v8 offset0:36 offset1:101
	s_waitcnt lgkmcnt(0)
	v_cvt_pk_bf16_f32 v2, v2, v3
	ds_read2_b32 v[6:7], v8 offset0:166 offset1:231
	s_waitcnt lgkmcnt(0)
	v_cvt_pk_bf16_f32 v3, v6, v7
	v_or_b32_e32 v6, s0, v45
	v_lshlrev_b32_e32 v96, 10, v6
	v_lshl_add_u64 v[6:7], v[4:5], 0, v[96:97]
	global_store_dwordx4 v[6:7], v[0:3], off
	ds_read2_b32 v[0:1], v43 offset0:48 offset1:113
	s_waitcnt lgkmcnt(0)
	v_cvt_pk_bf16_f32 v0, v0, v1
	ds_read2_b32 v[2:3], v43 offset0:178 offset1:243
	s_waitcnt lgkmcnt(0)
	v_cvt_pk_bf16_f32 v1, v2, v3
	ds_read2_b32 v[2:3], v8 offset0:52 offset1:117
	s_waitcnt lgkmcnt(0)
	v_cvt_pk_bf16_f32 v2, v2, v3
	ds_read2_b32 v[6:7], v8 offset0:182 offset1:247
	s_waitcnt lgkmcnt(0)
	v_cvt_pk_bf16_f32 v3, v6, v7
	v_or_b32_e32 v6, s0, v46
	v_lshlrev_b32_e32 v96, 10, v6
	v_lshl_add_u64 v[4:5], v[4:5], 0, v[96:97]
	global_store_dwordx4 v[4:5], v[0:3], off
	s_waitcnt lgkmcnt(0)

; #define LAS __attribute__((address_space(3)))
; __device__ __forceinline__ void transpose_item(const float* W, int N, const float* ks, bf16_t* WT, int ldo, int orow0, int k0, int n0, LAS float* scr, int lane) {
;     f32x4 v[8];
; #pragma unroll
;     for (int i = 0; i < 8; ++i) v[i] = *(const f32x4*)(W + (size_t)(k0 + i * 4 + (lane >> 4)) * N + n0 + 4 * (lane & 15));
; #pragma unroll
;     for (int i = 0; i < 8; ++i) { const int kk = i * 4 + (lane >> 4); const float sc = ks ? ks[k0 + kk] : 1.0f; LAS float* d = scr + kk * 65 + 4 * (lane & 15);
;         d[0] = v[i][0] * sc; d[1] = v[i][1] * sc; d[2] = v[i][2] * sc; d[3] = v[i][3] * sc; }
; __device__ __forceinline__ void convert_weights(const Params& p, LAS unsigned char* lds, int first, int last, int worker, int nworkers) {
;     ...
;         if (r < WI_IN) { const int kb = r / 52, nb = r % 52; transpose_item(p.w_in + (size_t)l * DM * INW, INW, p.norm_mix + l * DM, (bf16_t*)(wb + WO_IN), DM, nb * 64, kb * 32, nb * 64, scr, lane); continue; } r -= WI_IN;
.LBB0_643:
	s_andn2_b64 vcc, exec, s[0:1]
	s_cbranch_vccnz .LBB0_620
	s_mul_i32 s0, s16, 0x4ec5
	s_lshr_b32 s1, s0, 31
	s_ashr_i32 s0, s0, 20
	s_add_i32 s3, s0, s1
	s_mul_i32 s0, s3, 52
	v_readlane_b32 s52, v249, 4
	s_sub_i32 s0, s16, s0
	s_mul_i32 s1, s2, 0xd00000
	v_readlane_b32 s66, v249, 18
	s_sext_i32_i16 s16, s0
	s_mul_hi_i32 s0, s2, 0xd00000
	v_readlane_b32 s67, v249, 19
	s_add_u32 s18, s66, s1
	s_addc_u32 s19, s67, s0
	s_lshl_b32 s0, s2, 10
	s_ashr_i32 s1, s0, 31
	v_readlane_b32 s64, v249, 16
	s_lshl_b64 s[0:1], s[0:1], 2
	v_readlane_b32 s65, v249, 17
	s_add_u32 s8, s64, s0
	s_addc_u32 s9, s65, s1
	s_lshl_b32 s0, s16, 6
	s_ashr_i32 s1, s0, 31
	s_lshl_b32 s2, s3, 5
	s_lshl_b64 s[16:17], s[0:1], 2
	v_or_b32_e32 v40, s2, v32
	s_add_u32 s16, s18, s16
	s_addc_u32 s17, s19, s17
	v_lshlrev_b32_e32 v96, 2, v34
	v_mul_i32_i24_e32 v4, 0xd00, v40
	v_lshl_add_u64 v[0:1], s[16:17], 0, v[96:97]
	v_mul_hi_i32_i24_e32 v3, 0x3400, v40
	v_mul_i32_i24_e32 v2, 0x3400, v40
	v_ashrrev_i32_e32 v5, 31, v4
	v_lshl_add_u64 v[2:3], v[0:1], 0, v[2:3]
	v_lshl_add_u64 v[0:1], v[4:5], 2, v[0:1]
	s_mov_b32 s1, 0xd000
	v_add_co_u32_e32 v4, vcc, s1, v0
	s_mov_b32 s1, 0x1a000
	s_nop 0
	v_addc_co_u32_e32 v5, vcc, 0, v1, vcc
	global_load_dwordx4 v[28:31], v[2:3], off
	global_load_dwordx4 v[24:27], v[4:5], off
	v_add_co_u32_e32 v2, vcc, s1, v0
	s_mov_b32 s1, 0x27000
	s_nop 0
	v_addc_co_u32_e32 v3, vcc, 0, v1, vcc
	v_add_co_u32_e32 v4, vcc, s1, v0
	s_mov_b32 s1, 0x34000
	s_nop 0
	v_addc_co_u32_e32 v5, vcc, 0, v1, vcc
	global_load_dwordx4 v[20:23], v[2:3], off
	global_load_dwordx4 v[16:19], v[4:5], off
	v_add_co_u32_e32 v2, vcc, s1, v0
	v_mov_b32_e32 v38, 1.0
	s_nop 0
	v_addc_co_u32_e32 v3, vcc, 0, v1, vcc
	v_add_co_u32_e32 v4, vcc, 0x41000, v0
	v_mov_b32_e32 v42, 1.0
	s_nop 0
	v_addc_co_u32_e32 v5, vcc, 0, v1, vcc
	global_load_dwordx4 v[12:15], v[2:3], off
	global_load_dwordx4 v[8:11], v[4:5], off
	v_add_co_u32_e32 v2, vcc, 0x4e000, v0
	v_readlane_b32 s53, v249, 5
	s_nop 0
	v_addc_co_u32_e32 v3, vcc, 0, v1, vcc
	v_add_co_u32_e32 v0, vcc, 0x5b000, v0
	v_readlane_b32 s54, v249, 6
	s_nop 0
	v_addc_co_u32_e32 v1, vcc, 0, v1, vcc
	global_load_dwordx4 v[4:7], v[2:3], off
	s_nop 0
	global_load_dwordx4 v[0:3], v[0:1], off nt
	s_and_b64 vcc, exec, s[46:47]
	v_readlane_b32 s55, v249, 7
	v_readlane_b32 s56, v249, 8
	v_readlane_b32 s57, v249, 9
	v_readlane_b32 s58, v249, 10
	v_readlane_b32 s59, v249, 11
	v_readlane_b32 s60, v249, 12
	v_readlane_b32 s61, v249, 13
	v_readlane_b32 s62, v249, 14
	v_readlane_b32 s63, v249, 15
	s_cbranch_vccnz .LBB0_646
	v_ashrrev_i32_e32 v41, 31, v40
	v_lshl_add_u64 v[40:41], v[40:41], 2, s[8:9]
	global_load_dword v40, v[40:41], off
	s_ashr_i32 s3, s2, 31
	s_waitcnt vmcnt(0)
	v_pk_mul_f32 v[28:29], v[28:29], v[40:41] op_sel_hi:[1,0]
	v_pk_mul_f32 v[30:31], v[30:31], v[40:41] op_sel_hi:[1,0]
	v_lshl_add_u64 v[40:41], s[2:3], 0, v[32:33]
	v_lshl_add_u64 v[40:41], v[40:41], 2, s[8:9]
	global_load_dword v42, v[40:41], off offset:16

;     __device__ __forceinline__ void finish(const f32x4 x0, const f32x4 x1, int row, int col, float& s) const {
;         if (OUT_F32) { *(f32x4*)(out + (size_t)row * DM + col) = x0; *(f32x4*)(out + (size_t)row * DM + col + 4) = x1; }
;         else { u32x4 w; w.x = cvt_pk_bf16(x0[0], x0[1]); w.y = cvt_pk_bf16(x0[2], x0[3]); w.z = cvt_pk_bf16(x1[0], x1[1]); w.w = cvt_pk_bf16(x1[2], x1[3]); *(u32x4*)(XB + (size_t)row * DM + col) = w; }
;         s += (x0[0] * x0[0] + x0[1] * x0[1]) + (x0[2] * x0[2] + x0[3] * x0[3]) + (x1[0] * x1[0] + x1[1] * x1[1]) + (x1[2] * x1[2] + x1[3] * x1[3]);
;     }
;     __device__ __forceinline__ void operator()(AccT& acc, const Unit& u, int wr, int wc, int fr, int fq) const {
;         const int col0 = u.pn * 256 + wc * 32 + 8 * fq;
;         if constexpr (!RES_F32) {
;             u32x4 rb[2][4][2];
; #pragma unroll
;             for (int ai = 0; ai < 2; ++ai)
; #pragma unroll
;                 for (int m = 0; m < 4; ++m)
; #pragma unroll
;                     for (int bj = 0; bj < 2; ++bj) rb[ai][m][bj] = __builtin_nontemporal_load((const u32x4*)((const char*)XB + (unsigned)(((u.pm * 256 + ai * 128 + wr * 64 + m * 16 + fr) * DM + col0 + bj * 128) * 2)));
; #pragma unroll
;             for (int ai = 0; ai < 2; ++ai)
; #pragma unroll
;                 for (int m = 0; m < 4; ++m) {
;                     const int row = u.pm * 256 + ai * 128 + wr * 64 + m * 16 + fr; float s = 0.f;
; #pragma unroll
;                     for (int bj = 0; bj < 2; ++bj) { const u32x4 w = rb[ai][m][bj];
;                         finish((f32x4){bf_lo(w.x), bf_hi(w.x), bf_lo(w.y), bf_hi(w.y)} + acc[ai][bj][m][0], (f32x4){bf_lo(w.z), bf_hi(w.z), bf_lo(w.w), bf_hi(w.w)} + acc[ai][bj][m][1], row, col0 + bj * 128, s); }
;                     if (!OUT_F32) { s += __shfl_xor(s, 16); s += __shfl_xor(s, 32); if (fq == 0) atomicAdd(ssq_next + row, s); }
;                 }
;         } else {
; #pragma unroll
;             for (int ai = 0; ai < 2; ++ai) {
;                 f32x4 rv[4][2][2];
; #pragma unroll
;                 for (int m = 0; m < 4; ++m)
; #pragma unroll
;                     for (int bj = 0; bj < 2; ++bj) { const size_t o = (size_t)(u.pm * 256 + ai * 128 + wr * 64 + m * 16 + fr) * DM + col0 + bj * 128; rv[m][bj][0] = *(const f32x4*)(res + o); rv[m][bj][1] = *(const f32x4*)(res + o + 4); }
; #pragma unroll
.LBB0_927:
	s_lshl_b32 s0, s48, 8
	v_mov_b32_e32 v130, v212
	v_mov_b32_e32 v131, v213
	s_or_b32 s0, s0, s37
	v_readlane_b32 s56, v249, 4
	v_lshl_add_u32 v188, v131, 3, s0
	s_lshl_b32 s0, s45, 8
	s_add_i32 s0, s0, s33
	v_add_u32_e32 v190, s0, v130
	v_ashrrev_i32_e32 v189, 31, v188
	v_readlane_b32 s57, v249, 5
	v_ashrrev_i32_e32 v191, 31, v190
	v_cmp_eq_u32_e32 vcc, 0, v131
	v_lshl_add_u64 v[192:193], v[188:189], 2, s[56:57]
	v_lshlrev_b64 v[130:131], 12, v[190:191]
	v_lshl_add_u64 v[130:131], v[192:193], 0, v[130:131]
	global_load_dwordx4 v[216:219], v[130:131], off offset:16 nt
	global_load_dwordx4 v[230:233], v[130:131], off nt
	global_load_dwordx4 v[234:237], v[130:131], off offset:528 nt
	global_load_dwordx4 v[238:241], v[130:131], off offset:512 nt
	v_add_u32_e32 v210, 16, v190
	v_ashrrev_i32_e32 v211, 31, v210
	v_lshlrev_b64 v[130:131], 12, v[210:211]
	v_add_u32_e32 v208, 32, v190
	v_lshl_add_u64 v[130:131], v[192:193], 0, v[130:131]
	v_ashrrev_i32_e32 v209, 31, v208
	global_load_dwordx4 v[170:173], v[130:131], off offset:16 nt
	global_load_dwordx4 v[174:177], v[130:131], off nt
	global_load_dwordx4 v[162:165], v[130:131], off offset:528 nt
	global_load_dwordx4 v[166:169], v[130:131], off offset:512 nt
	v_lshlrev_b64 v[130:131], 12, v[208:209]
	v_add_u32_e32 v206, 48, v190
	v_lshl_add_u64 v[130:131], v[192:193], 0, v[130:131]
	v_ashrrev_i32_e32 v207, 31, v206
	global_load_dwordx4 v[154:157], v[130:131], off offset:16 nt
	global_load_dwordx4 v[158:161], v[130:131], off nt
	global_load_dwordx4 v[138:141], v[130:131], off offset:528 nt
	global_load_dwordx4 v[142:145], v[130:131], off offset:512 nt
	v_lshlrev_b64 v[130:131], 12, v[206:207]
	v_lshl_add_u64 v[134:135], v[192:193], 0, v[130:131]
	global_load_dwordx4 v[146:149], v[134:135], off offset:16 nt
	global_load_dwordx4 v[150:153], v[134:135], off nt
	global_load_dwordx4 v[130:133], v[134:135], off offset:528 nt
	s_nop 0
	global_load_dwordx4 v[134:137], v[134:135], off offset:512 nt
	v_lshlrev_b64 v[220:221], 11, v[190:191]
	v_lshl_add_u64 v[220:221], s[90:91], 0, v[220:221]
	v_lshl_add_u64 v[220:221], v[188:189], 1, v[220:221]
	v_readlane_b32 s58, v249, 6
	v_readlane_b32 s59, v249, 7
	v_readlane_b32 s60, v249, 8
	v_readlane_b32 s61, v249, 9
	v_readlane_b32 s62, v249, 10
	v_readlane_b32 s63, v249, 11
	v_readlane_b32 s64, v249, 12
	v_readlane_b32 s65, v249, 13
	v_readlane_b32 s66, v249, 14
	v_readlane_b32 s67, v249, 15
	v_readlane_b32 s68, v249, 16
	v_readlane_b32 s69, v249, 17
	v_readlane_b32 s70, v249, 18
	v_readlane_b32 s71, v249, 19
	s_waitcnt vmcnt(0)
	v_pk_add_f32 v[216:217], v[122:123], v[216:217]
	v_pk_add_f32 v[128:129], v[128:129], v[232:233]
	v_pk_add_f32 v[126:127], v[126:127], v[230:231]
	v_pk_add_f32 v[218:219], v[124:125], v[218:219]
	v_cvt_pk_bf16_f32 v122, v126, v127
	v_cvt_pk_bf16_f32 v123, v128, v129
	v_cvt_pk_bf16_f32 v124, v216, v217
	v_pk_add_f32 v[120:121], v[120:121], v[240:241]
	v_cvt_pk_bf16_f32 v125, v218, v219
	global_store_dwordx4 v[220:221], v[122:125], off
	v_pk_add_f32 v[118:119], v[118:119], v[238:239]
	s_nop 0
	v_mul_f32_e32 v122, v127, v127
	v_mul_f32_e32 v123, v129, v129
	v_fmac_f32_e32 v122, v126, v126
	v_fmac_f32_e32 v123, v128, v128
	v_add_f32_e32 v122, v122, v123
	v_mul_f32_e32 v123, v217, v217
	v_fmac_f32_e32 v123, v216, v216
	v_add_f32_e32 v122, v122, v123
	v_mul_f32_e32 v123, v219, v219
	v_fmac_f32_e32 v123, v218, v218
	v_pk_add_f32 v[124:125], v[114:115], v[234:235]
	v_cvt_pk_bf16_f32 v114, v118, v119
	v_cvt_pk_bf16_f32 v115, v120, v121
	v_add_f32_e32 v126, v123, v122
	v_pk_add_f32 v[122:123], v[116:117], v[236:237]
	v_cvt_pk_bf16_f32 v116, v124, v125
	s_nop 0
	v_cvt_pk_bf16_f32 v117, v122, v123
	global_store_dwordx4 v[220:221], v[114:117], off offset:256
	s_nop 1
	v_mul_f32_e32 v114, v119, v119
	v_mul_f32_e32 v115, v121, v121
	v_fmac_f32_e32 v114, v118, v118
	v_fmac_f32_e32 v115, v120, v120
	v_add_f32_e32 v114, v114, v115
	v_mul_f32_e32 v115, v125, v125
	v_fmac_f32_e32 v115, v124, v124
	v_add_f32_e32 v114, v114, v115
	v_mul_f32_e32 v115, v123, v123
	v_fmac_f32_e32 v115, v122, v122
	v_and_b32_e32 v116, 64, v225
	v_add_f32_e32 v114, v115, v114
	v_xor_b32_e32 v115, 16, v225
	v_add_u32_e32 v116, 64, v116
	v_cmp_lt_i32_e64 s[0:1], v115, v116
	v_add_f32_e32 v114, v126, v114
	s_nop 0
	v_cndmask_b32_e64 v115, v225, v115, s[0:1]
	v_lshlrev_b32_e32 v122, 2, v115
	ds_bpermute_b32 v115, v122, v114
	s_waitcnt lgkmcnt(0)
	v_add_f32_e32 v114, v114, v115
	v_xor_b32_e32 v115, 32, v225
	v_cmp_lt_i32_e64 s[0:1], v115, v116
	s_nop 1
	v_cndmask_b32_e64 v115, v225, v115, s[0:1]
	v_lshlrev_b32_e32 v123, 2, v115
	ds_bpermute_b32 v115, v123, v114
	s_and_saveexec_b64 s[0:1], vcc
	s_cbranch_execz .LBB0_929
	v_lshl_add_u64 v[116:117], v[190:191], 2, s[2:3]
	s_waitcnt lgkmcnt(0)
	v_add_f32_e32 v114, v114, v115
	global_atomic_add_f32 v[116:117], v114, off

; __device__ __forceinline__ unsigned cvt_pk_bf16(float lo, float hi) { unsigned r; asm volatile("v_cvt_pk_bf16_f32 %0, %1, %2" : "=v"(r) : "v"(lo), "v"(hi)); return r; }
;     __device__ __forceinline__ void finish(const f32x4 x0, const f32x4 x1, int row, int col, float& s) const {
;         if (OUT_F32) { *(f32x4*)(out + (size_t)row * DM + col) = x0; *(f32x4*)(out + (size_t)row * DM + col + 4) = x1; }
;         else { u32x4 w; w.x = cvt_pk_bf16(x0[0], x0[1]); w.y = cvt_pk_bf16(x0[2], x0[3]); w.z = cvt_pk_bf16(x1[0], x1[1]); w.w = cvt_pk_bf16(x1[2], x1[3]); *(u32x4*)(XB + (size_t)row * DM + col) = w; }
;         s += (x0[0] * x0[0] + x0[1] * x0[1]) + (x0[2] * x0[2] + x0[3] * x0[3]) + (x1[0] * x1[0] + x1[1] * x1[1]) + (x1[2] * x1[2] + x1[3] * x1[3]);
;     }
;     __device__ __forceinline__ void operator()(AccT& acc, const Unit& u, int wr, int wc, int fr, int fq) const {
;     ...
; #pragma unroll
;             for (int ai = 0; ai < 2; ++ai) {
;                 f32x4 rv[4][2][2];
; #pragma unroll
;                 for (int m = 0; m < 4; ++m)
; #pragma unroll
;                     for (int bj = 0; bj < 2; ++bj) { const size_t o = (size_t)(u.pm * 256 + ai * 128 + wr * 64 + m * 16 + fr) * DM + col0 + bj * 128; rv[m][bj][0] = *(const f32x4*)(res + o); rv[m][bj][1] = *(const f32x4*)(res + o + 4); }
; #pragma unroll
;                 for (int m = 0; m < 4; ++m) {
;                     const int row = u.pm * 256 + ai * 128 + wr * 64 + m * 16 + fr; float s = 0.f;
; #pragma unroll
;                     for (int bj = 0; bj < 2; ++bj) finish(rv[m][bj][0] + acc[ai][bj][m][0], rv[m][bj][1] + acc[ai][bj][m][1], row, col0 + bj * 128, s);
;                     if (!OUT_F32) { s += __shfl_xor(s, 16); s += __shfl_xor(s, 32); if (fq == 0) atomicAdd(ssq_next + row, s); }
.LBB0_935:
	s_or_b64 exec, exec, s[0:1]
	v_add_u32_e32 v120, 0x80, v190
	v_ashrrev_i32_e32 v121, 31, v120
	s_waitcnt lgkmcnt(0)
	v_lshlrev_b64 v[64:65], 12, v[120:121]
	v_lshl_add_u64 v[64:65], v[192:193], 0, v[64:65]
	global_load_dwordx4 v[124:127], v[64:65], off nt
	global_load_dwordx4 v[128:131], v[64:65], off offset:16 nt
	global_load_dwordx4 v[132:135], v[64:65], off offset:512 nt
	global_load_dwordx4 v[136:139], v[64:65], off offset:528 nt
	v_add_u32_e32 v118, 0x90, v190
	v_add_u32_e32 v116, 0xa0, v190
	v_add_u32_e32 v114, 0xb0, v190
	v_ashrrev_i32_e32 v119, 31, v118
	v_ashrrev_i32_e32 v117, 31, v116
	v_ashrrev_i32_e32 v115, 31, v114
	v_lshlrev_b64 v[64:65], 12, v[118:119]
	v_lshlrev_b64 v[66:67], 12, v[116:117]
	v_lshlrev_b64 v[68:69], 12, v[114:115]
	v_lshl_add_u64 v[64:65], v[192:193], 0, v[64:65]
	v_lshl_add_u64 v[66:67], v[192:193], 0, v[66:67]
	v_lshl_add_u64 v[68:69], v[192:193], 0, v[68:69]
	global_load_dwordx4 v[106:109], v[64:65], off offset:16 nt
	global_load_dwordx4 v[110:113], v[64:65], off nt
	global_load_dwordx4 v[98:101], v[64:65], off offset:528 nt
	global_load_dwordx4 v[102:105], v[64:65], off offset:512 nt
	global_load_dwordx4 v[88:91], v[66:67], off offset:16 nt
	global_load_dwordx4 v[92:95], v[66:67], off nt
	global_load_dwordx4 v[80:83], v[66:67], off offset:528 nt
	global_load_dwordx4 v[84:87], v[66:67], off offset:512 nt
	global_load_dwordx4 v[72:75], v[68:69], off offset:16 nt
	global_load_dwordx4 v[76:79], v[68:69], off nt
	s_nop 0
	global_load_dwordx4 v[64:67], v[68:69], off offset:528 nt
	s_nop 0
	global_load_dwordx4 v[68:71], v[68:69], off offset:512 nt
	v_lshlrev_b64 v[140:141], 11, v[120:121]
	s_waitcnt vmcnt(0)
	v_pk_add_f32 v[62:63], v[62:63], v[126:127]
	v_pk_add_f32 v[60:61], v[60:61], v[124:125]
	v_pk_add_f32 v[54:55], v[54:55], v[134:135]
	v_pk_add_f32 v[52:53], v[52:53], v[132:133]
	v_pk_add_f32 v[58:59], v[58:59], v[130:131]
	v_pk_add_f32 v[56:57], v[56:57], v[128:129]
	v_pk_add_f32 v[126:127], v[48:49], v[136:137]
	v_cvt_pk_bf16_f32 v48, v60, v61
	v_cvt_pk_bf16_f32 v49, v62, v63
	v_mul_f32_e32 v61, v61, v61
	v_mul_f32_e32 v63, v63, v63
	v_mul_f32_e32 v128, v53, v53
	v_mul_f32_e32 v129, v55, v55
	v_pk_add_f32 v[124:125], v[50:51], v[138:139]
	v_cvt_pk_bf16_f32 v50, v56, v57
	v_cvt_pk_bf16_f32 v51, v58, v59
	v_mul_f32_e32 v57, v57, v57
	v_mul_f32_e32 v59, v59, v59
	v_mul_f32_e32 v130, v127, v127
	v_fmac_f32_e32 v61, v60, v60
	v_fmac_f32_e32 v63, v62, v62
	v_fmac_f32_e32 v128, v52, v52
	v_fmac_f32_e32 v129, v54, v54
	v_mul_f32_e32 v131, v125, v125
	v_fmac_f32_e32 v57, v56, v56
	v_fmac_f32_e32 v59, v58, v58
	v_fmac_f32_e32 v130, v126, v126
	v_add_f32_e32 v56, v61, v63
	v_add_f32_e32 v58, v128, v129
	v_fmac_f32_e32 v131, v124, v124
	v_add_f32_e32 v56, v56, v57
	v_add_f32_e32 v57, v58, v130
	v_add_f32_e32 v56, v59, v56
	v_add_f32_e32 v57, v131, v57
	v_add_f32_e32 v58, v56, v57
	ds_bpermute_b32 v59, v122, v58
	v_lshl_add_u64 v[56:57], s[90:91], 0, v[140:141]
	v_lshl_add_u64 v[56:57], v[188:189], 1, v[56:57]
	global_store_dwordx4 v[56:57], v[48:51], off
	s_waitcnt lgkmcnt(0)
	s_nop 0
	v_add_f32_e32 v48, v58, v59
	ds_bpermute_b32 v49, v123, v48
	v_cvt_pk_bf16_f32 v50, v52, v53
	v_cvt_pk_bf16_f32 v51, v54, v55
	v_cvt_pk_bf16_f32 v52, v126, v127
	v_cvt_pk_bf16_f32 v53, v124, v125
	global_store_dwordx4 v[56:57], v[50:53], off offset:256
	s_and_saveexec_b64 s[0:1], vcc
	s_cbranch_execz .LBB0_937
	v_lshl_add_u64 v[50:51], v[120:121], 2, s[2:3]
	s_waitcnt lgkmcnt(0)
	v_add_f32_e32 v48, v48, v49
	global_atomic_add_f32 v[50:51], v48, off
